# SWA tile body software-pipelined at (half-tile, head) unit granularity: QK of unit u+1, exp/sum/cvt of unit u, PV of unit u-1 interleaved; VGPR 242->256
# baseline (speedup 1.0000x reference)
; #define LAS __attribute__((address_space(3)))
; __device__ __forceinline__ void drain_wait() { asm volatile("s_waitcnt vmcnt(0)" ::: "memory"); __syncthreads(); }
; __device__ __forceinline__ void swa_phase(LAS unsigned char* lds, const bf16_t* Q, const bf16_t* K, const bf16_t* V, bf16_t* Ob, const float* sink, float negb) {
;     ...
;         const int b = item >> 8, kvh = (item >> 6) & 3, tb = item & 63;
;         const size_t ctx0 = (size_t)(MLAT + b * NCTX), lat0 = (size_t)(b * SEQ);
;         const int i_lo = tb == 0 ? 2 : 0, i_hi = tb == 63 ? 4 : 6;
;         const int NT = 4 + (i_hi - i_lo);
;         const DmaLane dl = dma_lane(256, kvh * 64, w, lane);
;     ...
;         dma_tile<1>(lds, K, V, SW_ROW0(0), 256, dl, w);
;         dma_tile<1>(lds + SW_BUF, K, V, SW_ROW0(1), 256, dl, w);
;         dma_tile<1>(lds + 2 * SW_BUF, K, V, SW_ROW0(2), 256, dl, w);
;         const int tq = 128 * tb + 16 * w;
;         const size_t qrow = (size_t)(b * SEQ + tq + l15);
;         bf16x8 qf[4][2];
; #pragma unroll
;         for (int grp = 0; grp < 4; ++grp)
; #pragma unroll
;             for (int ds = 0; ds < 2; ++ds) qf[grp][ds] = *(const bf16x8*)(Q + qrow * DM + (4 * kvh + grp) * 64 + 32 * ds + 8 * g);
;         f32x4 O[4][4]; float ls[4];
; #pragma unroll
;         for (int grp = 0; grp < 4; ++grp) { ls[grp] = 0.f;
; #pragma unroll
;             for (int db = 0; db < 4; ++db) O[grp][db] = (f32x4){0.f, 0.f, 0.f, 0.f}; }
;         drain_wait();
;         for (int t = 0; t < 4; ++t) {
;             dma_tile<1>(lds + ((t + 3) & 3) * SW_BUF, K, V, SW_ROW0(t + 3), 256, dl, w);
;             const LAS unsigned char* buf = lds + (t & 3) * SW_BUF;
;             full_tile<0, 2, 2>(O, ls, qf, negb, buf, buf + 8192, lane, 0);
.LBB0_350:
	s_cmp_lt_i32 s6, 0
	s_cbranch_scc1 .LBB0_357
	s_and_b32 s0, s6, 0x7fffff00
	s_add_i32 s82, s0, 0x8000
	s_lshl_b32 s0, s6, 5
	s_bfe_u32 s42, s6, 0x20006
	s_and_b32 s12, s6, 63
	s_and_b32 s43, s0, 0x7fffe000
	s_cmp_eq_u32 s12, 0
	s_cselect_b32 s7, 2, 0
	s_cmp_eq_u32 s12, 63
	s_cselect_b32 s0, 4, 6
	s_sub_i32 s44, s0, s7
	s_lshl_b64 s[8:9], s[82:83], 9
	s_add_u32 s0, s67, s8
	s_addc_u32 s1, s4, s9
	v_lshl_or_b32 v4, s42, 7, v188
	s_add_u32 s10, s5, s8
	v_or_b32_e32 v212, v4, v189
	s_addc_u32 s11, s58, s9
	s_add_i32 s6, s40, 0x2000
	s_mov_b32 s13, m0
	s_mov_b32 m0, s40
	s_nop 0
	global_load_lds_dwordx4 v212, s[0:1]
	s_mov_b32 m0, s13
	v_or_b32_e32 v213, v4, v190
	s_mov_b32 s0, m0
	s_mov_b32 m0, s6
	s_nop 0
	global_load_lds_dwordx4 v213, s[10:11]
	s_mov_b32 m0, s0
	s_or_b32 s6, s8, 0x8000
	s_add_u32 s0, s67, s6
	s_addc_u32 s1, s4, s9
	s_add_u32 s10, s5, s6
	s_addc_u32 s11, s58, s9
	s_add_i32 s6, s40, 0x4000
	s_mov_b32 s14, m0
	s_mov_b32 m0, s6
	s_nop 0
	global_load_lds_dwordx4 v212, s[0:1]
	s_mov_b32 m0, s14
	s_add_i32 s13, s40, 0x6000
	s_mov_b32 s0, m0
	s_mov_b32 m0, s13
	s_nop 0
	global_load_lds_dwordx4 v213, s[10:11]
	s_mov_b32 m0, s0
	s_or_b32 s6, s8, 0x10000
	s_add_u32 s0, s67, s6
	s_addc_u32 s1, s4, s9
	s_add_u32 s10, s5, s6
	s_addc_u32 s11, s58, s9
	s_add_i32 s6, s40, 0x8000
	s_mov_b32 s14, m0
	s_mov_b32 m0, s6
	s_nop 0
	global_load_lds_dwordx4 v212, s[0:1]
	s_mov_b32 m0, s14
	s_add_i32 s13, s40, 0xa000
	s_mov_b32 s0, m0
	s_mov_b32 m0, s13
	s_nop 0
	global_load_lds_dwordx4 v213, s[10:11]
	s_mov_b32 m0, s0
	s_lshl_b32 s45, s12, 7
	s_add_i32 s0, s45, s39
	s_add_i32 s1, s0, s43
	v_or_b32_e32 v4, s1, v187
	v_ashrrev_i32_e32 v5, 31, v4
	v_lshlrev_b64 v[126:127], 11, v[4:5]
	v_lshl_add_u64 v[4:5], v[122:123], 0, v[126:127]
	s_lshl_b32 s36, s42, 9
	s_mov_b32 s37, s83
	v_lshl_add_u64 v[32:33], v[4:5], 0, s[36:37]
	global_load_dwordx4 v[4:7], v[32:33], off
	global_load_dwordx4 v[8:11], v[32:33], off offset:128
	global_load_dwordx4 v[12:15], v[32:33], off offset:64
	global_load_dwordx4 v[16:19], v[32:33], off offset:192
	global_load_dwordx4 v[20:23], v[32:33], off offset:256
	global_load_dwordx4 v[24:27], v[32:33], off offset:320
	global_load_dwordx4 v[28:31], v[32:33], off offset:384
	s_nop 0
	global_load_dwordx4 v[32:35], v[32:33], off offset:448
	s_lshl_b32 s37, s42, 8
	s_add_i32 s46, s44, 4
	s_or_b32 s1, s8, 0x18000
	s_add_u32 s10, s67, s1
	s_addc_u32 s11, s4, s9
	s_add_u32 s8, s5, s1
	s_addc_u32 s9, s58, s9
	s_add_i32 s1, s40, 0xc000
	s_waitcnt vmcnt(0)
	s_barrier
	s_mov_b32 s12, m0
	s_mov_b32 m0, s1
	s_nop 0
	global_load_lds_dwordx4 v212, s[10:11]
	s_mov_b32 m0, s12
	v_add_u32_e32 v91, v154, v192
	s_add_i32 s6, s40, 0xe000
	s_mov_b32 s1, m0
	s_mov_b32 m0, s6
	s_nop 0
	global_load_lds_dwordx4 v213, s[8:9]
	s_mov_b32 m0, s1
	v_mov_b32_e32 v64, 0
	v_mov_b32_e32 v65, 0
	v_mov_b32_e32 v66, 0
	v_mov_b32_e32 v67, 0
	v_mov_b32_e32 v60, 0
	v_mov_b32_e32 v61, 0
	v_mov_b32_e32 v62, 0
	v_mov_b32_e32 v63, 0
	v_mov_b32_e32 v56, 0
	v_mov_b32_e32 v57, 0
	v_mov_b32_e32 v58, 0
	v_mov_b32_e32 v59, 0
	v_mov_b32_e32 v52, 0
	v_mov_b32_e32 v53, 0
	v_mov_b32_e32 v54, 0
	v_mov_b32_e32 v55, 0
	v_mov_b32_e32 v131, 0
	v_mov_b32_e32 v48, 0
	v_mov_b32_e32 v49, 0
	v_mov_b32_e32 v50, 0
	v_mov_b32_e32 v51, 0
	v_mov_b32_e32 v44, 0
	v_mov_b32_e32 v45, 0
	v_mov_b32_e32 v46, 0
	v_mov_b32_e32 v47, 0
	v_mov_b32_e32 v40, 0
	v_mov_b32_e32 v41, 0
	v_mov_b32_e32 v42, 0
	v_mov_b32_e32 v43, 0
	v_mov_b32_e32 v36, 0
	v_mov_b32_e32 v37, 0
	v_mov_b32_e32 v38, 0
	v_mov_b32_e32 v39, 0
	v_mov_b32_e32 v130, 0
	v_mov_b32_e32 v72, 0
	v_mov_b32_e32 v73, 0
	v_mov_b32_e32 v74, 0
	v_mov_b32_e32 v75, 0
	v_mov_b32_e32 v84, 0
	v_mov_b32_e32 v85, 0
	v_mov_b32_e32 v86, 0
	v_mov_b32_e32 v87, 0
	v_mov_b32_e32 v88, 0
	v_mov_b32_e32 v89, 0
	v_mov_b32_e32 v90, 0
	v_mov_b32_e32 v91, 0
	v_mov_b32_e32 v96, 0
	v_mov_b32_e32 v97, 0
	v_mov_b32_e32 v98, 0
	v_mov_b32_e32 v99, 0
	v_mov_b32_e32 v129, 0
	v_mov_b32_e32 v68, 0
	v_mov_b32_e32 v69, 0
	v_mov_b32_e32 v70, 0
	v_mov_b32_e32 v71, 0
	v_mov_b32_e32 v76, 0
	v_mov_b32_e32 v77, 0
	v_mov_b32_e32 v78, 0
	v_mov_b32_e32 v79, 0
	v_mov_b32_e32 v80, 0
	v_mov_b32_e32 v81, 0
	v_mov_b32_e32 v82, 0
	v_mov_b32_e32 v83, 0
	v_mov_b32_e32 v92, 0
	v_mov_b32_e32 v93, 0
	v_mov_b32_e32 v94, 0
	v_mov_b32_e32 v95, 0
	v_mov_b32_e32 v128, 0
	s_lshl_b32 s47, s7, 6
	s_add_i32 s7, s45, s47
	s_addk_i32 s7, 0xff80
	s_ashr_i32 s8, s7, 31
	s_add_u32 s7, s43, s7
	s_addc_u32 s8, 0, s8
	s_mov_b32 s1, 0
	s_mov_b32 s6, 4
	s_mov_b32 s34, 0
	v_add_u32_e32 v100, s34, v191
	v_add3_u32 v135, s34, v203, v198
	v_add_u32_e32 v102, v100, v193
	v_add_u32_e32 v100, v100, v192
	ds_read_b128 v[160:163], v100
	ds_read_b128 v[164:167], v102
	ds_read_b128 v[168:171], v100 offset:2048
	ds_read_b128 v[172:175], v102 offset:2048
	ds_read_b128 v[104:107], v100 offset:4096
	ds_read_b128 v[108:111], v102 offset:4096
	ds_read_b128 v[112:115], v100 offset:6144
	ds_read_b128 v[116:119], v102 offset:6144
	v_add_u32_e32 v103, v135, v199
	v_add_u32_e32 v133, v135, v200
	v_add_u32_e32 v134, v135, v201
	v_add_u32_e32 v135, v135, v202
	s_waitcnt lgkmcnt(4)
; #define LAS __attribute__((address_space(3)))
;     const int l15 = lane & 15, g = lane >> 4, q4 = l15 >> 2;
;     const LAS unsigned char* kb0 = Kt + l15 * 128;
;     const int kx0 = ((g) ^ (l15 & 7)) << 4, kx1 = ((4 + g) ^ (l15 & 7)) << 4;
;     const LAS unsigned char* vrow = Vt + (4 * g + q4) * 128 + (lane & 3) * 8;
;     const int swz = (2 * (g & 1) + (q4 >> 1)) & 3;
;     const f32x4 cinit = (f32x4){negb, negb, negb, negb};
; #pragma unroll
;     for (int gh = 0; gh < 4 / GPB; ++gh) {
;         f32x4 S[GPB][4];
; #pragma unroll
;         for (int kb = 0; kb < 4; ++kb) {
;             const bf16x8 kf0 = *(const LAS bf16x8*)(kb0 + (16 * kb) * 128 + kx0), kf1 = *(const LAS bf16x8*)(kb0 + (16 * kb) * 128 + kx1);
; #pragma unroll
;             for (int gi = 0; gi < GPB; ++gi) { S[gi][kb] = __builtin_amdgcn_mfma_f32_16x16x32_bf16(kf0, qf[GPB * gh + gi][0], cinit, 0, 0, 0);
;                 S[gi][kb] = __builtin_amdgcn_mfma_f32_16x16x32_bf16(kf1, qf[GPB * gh + gi][1], S[gi][kb], 0, 0, 0); } }
;         bf16x8 pf[GPB][2];
; #pragma unroll
;         for (int gi = 0; gi < GPB; ++gi) {
;             if (MASK) {
; #pragma unroll
;                 for (int kb = 0; kb < 4; ++kb)
; #pragma unroll
;                     for (int i = 0; i < 4; ++i) { const int rel = rel0 + 16 * kb + 4 * g + i; S[gi][kb][i] = ((unsigned)(rel + 128) > 256u) ? NEGBIG : S[gi][kb][i]; }
;             }
;             ls[GPB * gh + gi] += exp_step<4>(S[gi]);
;             pf[gi][0] = pack8(S[gi][0], S[gi][1]); pf[gi][1] = pack8(S[gi][2], S[gi][3]);
;         }
; #pragma unroll
;         for (int kc = 0; kc < 2; ++kc)
; #pragma unroll
;             for (int db = 0; db < 4; ++db) {
;                 const LAS unsigned char* va = vrow + ((db ^ swz) << 5) + (32 * kc) * 128;
;                 const bf16x8 vf = cat8(vtr(va), vtr(va + 16 * 128));
; #pragma unroll
;                 for (int gi = 0; gi < GPB; ++gi) O[GPB * gh + gi][db] = __builtin_amdgcn_mfma_f32_16x16x32_bf16(vf, pf[gi][kc], O[GPB * gh + gi][db], 0, 0, 0);
;             }
;         if (SB == 1) __builtin_amdgcn_sched_barrier(0); else if (SB == 2) __builtin_amdgcn_sched_barrier(0x108);
;     }
; }
; __device__ __forceinline__ void swa_phase(LAS unsigned char* lds, const bf16_t* Q, const bf16_t* K, const bf16_t* V, bf16_t* Ob, const float* sink, float negb) {
;     ...
;         for (int t = 0; t < 4; ++t) {
	v_mfma_f32_16x16x32_bf16 v[136:139], v[160:163], v[4:7], v[0:3]
	v_mfma_f32_16x16x32_bf16 v[140:143], v[168:171], v[4:7], v[0:3]
	v_mfma_f32_16x16x32_bf16 v[136:139], v[164:167], v[12:15], v[136:139]
	v_mfma_f32_16x16x32_bf16 v[140:143], v[172:175], v[12:15], v[140:143]
	ds_read_b64_tr_b16 v[216:217], v103 offset:8192
	ds_read_b64_tr_b16 v[218:219], v103 offset:10240
	ds_read_b64_tr_b16 v[220:221], v133 offset:8192
	ds_read_b64_tr_b16 v[222:223], v133 offset:10240
	ds_read_b64_tr_b16 v[224:225], v134 offset:8192
	ds_read_b64_tr_b16 v[226:227], v134 offset:10240
	ds_read_b64_tr_b16 v[228:229], v135 offset:8192
	ds_read_b64_tr_b16 v[230:231], v135 offset:10240
	v_mfma_f32_16x16x32_bf16 v[176:179], v[160:163], v[8:11], v[0:3]
	v_exp_f32_e32 v136, v136
	v_exp_f32_e32 v137, v137
	v_exp_f32_e32 v138, v138
	v_add_f32_e32 v144, v136, v137
	v_mfma_f32_16x16x32_bf16 v[232:235], v[168:171], v[8:11], v[0:3]
	v_exp_f32_e32 v139, v139
	v_add_f32_e32 v144, v144, v138
	v_exp_f32_e32 v140, v140
	v_add_f32_e32 v144, v144, v139
	v_mfma_f32_16x16x32_bf16 v[176:179], v[164:167], v[16:19], v[176:179]
	v_exp_f32_e32 v141, v141
	v_add_f32_e32 v144, v144, v140
	v_exp_f32_e32 v142, v142
	v_add_f32_e32 v144, v144, v141
	v_cvt_pk_bf16_f32 v136, v136, v137
	v_mfma_f32_16x16x32_bf16 v[232:235], v[172:175], v[16:19], v[232:235]
	v_exp_f32_e32 v143, v143
	v_add_f32_e32 v144, v144, v142
	v_cvt_pk_bf16_f32 v137, v138, v139
	v_cvt_pk_bf16_f32 v138, v140, v141
	v_cvt_pk_bf16_f32 v139, v142, v143
	v_add_f32_e32 v144, v144, v143
	v_add_f32_e32 v131, v131, v144
	s_waitcnt lgkmcnt(0)
	v_mfma_f32_16x16x32_bf16 v[244:247], v[160:163], v[20:23], v[0:3]
	v_exp_f32_e32 v176, v176
	v_exp_f32_e32 v177, v177
	v_mfma_f32_16x16x32_bf16 v[248:251], v[168:171], v[20:23], v[0:3]
	v_exp_f32_e32 v178, v178
	v_add_f32_e32 v144, v176, v177
	v_mfma_f32_16x16x32_bf16 v[244:247], v[164:167], v[24:27], v[244:247]
	v_exp_f32_e32 v179, v179
	v_add_f32_e32 v144, v144, v178
	v_mfma_f32_16x16x32_bf16 v[248:251], v[172:175], v[24:27], v[248:251]
	v_exp_f32_e32 v232, v232
	v_add_f32_e32 v144, v144, v179
	v_mfma_f32_16x16x32_bf16 v[64:67], v[216:219], v[136:139], v[64:67]
	v_exp_f32_e32 v233, v233
	v_add_f32_e32 v144, v144, v232
	v_mfma_f32_16x16x32_bf16 v[60:63], v[220:223], v[136:139], v[60:63]
	v_exp_f32_e32 v234, v234
	v_add_f32_e32 v144, v144, v233
	v_cvt_pk_bf16_f32 v176, v176, v177
	v_mfma_f32_16x16x32_bf16 v[56:59], v[224:227], v[136:139], v[56:59]
	v_exp_f32_e32 v235, v235
	v_add_f32_e32 v144, v144, v234
	v_cvt_pk_bf16_f32 v177, v178, v179
	v_mfma_f32_16x16x32_bf16 v[52:55], v[228:231], v[136:139], v[52:55]
	v_cvt_pk_bf16_f32 v178, v232, v233
	v_cvt_pk_bf16_f32 v179, v234, v235
	v_add_f32_e32 v144, v144, v235
	v_add_f32_e32 v130, v130, v144
	v_mfma_f32_16x16x32_bf16 v[136:139], v[160:163], v[28:31], v[0:3]
	v_exp_f32_e32 v244, v244
	v_exp_f32_e32 v245, v245
	v_mfma_f32_16x16x32_bf16 v[140:143], v[168:171], v[28:31], v[0:3]
	v_exp_f32_e32 v246, v246
	v_add_f32_e32 v144, v244, v245
	v_mfma_f32_16x16x32_bf16 v[136:139], v[164:167], v[32:35], v[136:139]
	v_exp_f32_e32 v247, v247
	v_add_f32_e32 v144, v144, v246
	v_mfma_f32_16x16x32_bf16 v[140:143], v[172:175], v[32:35], v[140:143]
	v_exp_f32_e32 v248, v248
	v_add_f32_e32 v144, v144, v247
	v_mfma_f32_16x16x32_bf16 v[48:51], v[216:219], v[176:179], v[48:51]
	v_exp_f32_e32 v249, v249
	v_add_f32_e32 v144, v144, v248
	v_mfma_f32_16x16x32_bf16 v[44:47], v[220:223], v[176:179], v[44:47]
	v_exp_f32_e32 v250, v250
	v_add_f32_e32 v144, v144, v249
	v_cvt_pk_bf16_f32 v244, v244, v245
	v_mfma_f32_16x16x32_bf16 v[40:43], v[224:227], v[176:179], v[40:43]
	v_exp_f32_e32 v251, v251
	v_add_f32_e32 v144, v144, v250
	v_cvt_pk_bf16_f32 v245, v246, v247
	v_mfma_f32_16x16x32_bf16 v[36:39], v[228:231], v[176:179], v[36:39]
	v_cvt_pk_bf16_f32 v246, v248, v249
	v_cvt_pk_bf16_f32 v247, v250, v251
	v_add_f32_e32 v144, v144, v251
	v_add_f32_e32 v129, v129, v144
	ds_read_b64_tr_b16 v[160:161], v103 offset:12288
	ds_read_b64_tr_b16 v[162:163], v103 offset:14336
	ds_read_b64_tr_b16 v[164:165], v133 offset:12288
	ds_read_b64_tr_b16 v[166:167], v133 offset:14336
	ds_read_b64_tr_b16 v[168:169], v134 offset:12288
	ds_read_b64_tr_b16 v[170:171], v134 offset:14336
	ds_read_b64_tr_b16 v[172:173], v135 offset:12288
	ds_read_b64_tr_b16 v[174:175], v135 offset:14336
	v_mfma_f32_16x16x32_bf16 v[176:179], v[104:107], v[4:7], v[0:3]
	v_exp_f32_e32 v136, v136
	v_exp_f32_e32 v137, v137
	v_mfma_f32_16x16x32_bf16 v[232:235], v[112:115], v[4:7], v[0:3]
	v_exp_f32_e32 v138, v138
	v_add_f32_e32 v144, v136, v137
	v_mfma_f32_16x16x32_bf16 v[176:179], v[108:111], v[12:15], v[176:179]
	v_exp_f32_e32 v139, v139
	v_add_f32_e32 v144, v144, v138
	v_mfma_f32_16x16x32_bf16 v[232:235], v[116:119], v[12:15], v[232:235]
	v_exp_f32_e32 v140, v140
	v_add_f32_e32 v144, v144, v139
	v_mfma_f32_16x16x32_bf16 v[72:75], v[216:219], v[244:247], v[72:75]
	v_exp_f32_e32 v141, v141
	v_add_f32_e32 v144, v144, v140
	v_mfma_f32_16x16x32_bf16 v[84:87], v[220:223], v[244:247], v[84:87]
	v_exp_f32_e32 v142, v142
	v_add_f32_e32 v144, v144, v141
	v_cvt_pk_bf16_f32 v136, v136, v137
	v_mfma_f32_16x16x32_bf16 v[88:91], v[224:227], v[244:247], v[88:91]
	v_exp_f32_e32 v143, v143
	v_add_f32_e32 v144, v144, v142
	v_cvt_pk_bf16_f32 v137, v138, v139
	v_mfma_f32_16x16x32_bf16 v[96:99], v[228:231], v[244:247], v[96:99]
	v_cvt_pk_bf16_f32 v138, v140, v141
	v_cvt_pk_bf16_f32 v139, v142, v143
	v_add_f32_e32 v144, v144, v143
	v_add_f32_e32 v128, v128, v144
	v_mfma_f32_16x16x32_bf16 v[244:247], v[104:107], v[8:11], v[0:3]
	v_exp_f32_e32 v176, v176
	v_exp_f32_e32 v177, v177
	v_mfma_f32_16x16x32_bf16 v[248:251], v[112:115], v[8:11], v[0:3]
	v_exp_f32_e32 v178, v178
	v_add_f32_e32 v144, v176, v177
	v_mfma_f32_16x16x32_bf16 v[244:247], v[108:111], v[16:19], v[244:247]
	v_exp_f32_e32 v179, v179
	v_add_f32_e32 v144, v144, v178
	v_mfma_f32_16x16x32_bf16 v[248:251], v[116:119], v[16:19], v[248:251]
	v_exp_f32_e32 v232, v232
	v_add_f32_e32 v144, v144, v179
	v_mfma_f32_16x16x32_bf16 v[68:71], v[216:219], v[136:139], v[68:71]
	v_exp_f32_e32 v233, v233
	v_add_f32_e32 v144, v144, v232
	v_mfma_f32_16x16x32_bf16 v[76:79], v[220:223], v[136:139], v[76:79]
	v_exp_f32_e32 v234, v234
	v_add_f32_e32 v144, v144, v233
	v_cvt_pk_bf16_f32 v176, v176, v177
	v_mfma_f32_16x16x32_bf16 v[80:83], v[224:227], v[136:139], v[80:83]
	v_exp_f32_e32 v235, v235
	v_add_f32_e32 v144, v144, v234
	v_cvt_pk_bf16_f32 v177, v178, v179
	v_mfma_f32_16x16x32_bf16 v[92:95], v[228:231], v[136:139], v[92:95]
	v_cvt_pk_bf16_f32 v178, v232, v233
	v_cvt_pk_bf16_f32 v179, v234, v235
	v_add_f32_e32 v144, v144, v235
	v_add_f32_e32 v131, v131, v144
	s_waitcnt lgkmcnt(0)
; #define LAS __attribute__((address_space(3)))
;     const int l15 = lane & 15, g = lane >> 4, q4 = l15 >> 2;
;     const LAS unsigned char* kb0 = Kt + l15 * 128;
;     const int kx0 = ((g) ^ (l15 & 7)) << 4, kx1 = ((4 + g) ^ (l15 & 7)) << 4;
;     const LAS unsigned char* vrow = Vt + (4 * g + q4) * 128 + (lane & 3) * 8;
;     const int swz = (2 * (g & 1) + (q4 >> 1)) & 3;
;     const f32x4 cinit = (f32x4){negb, negb, negb, negb};
; #pragma unroll
;     for (int gh = 0; gh < 4 / GPB; ++gh) {
;         f32x4 S[GPB][4];
; #pragma unroll
;         for (int kb = 0; kb < 4; ++kb) {
;             const bf16x8 kf0 = *(const LAS bf16x8*)(kb0 + (16 * kb) * 128 + kx0), kf1 = *(const LAS bf16x8*)(kb0 + (16 * kb) * 128 + kx1);
; #pragma unroll
;             for (int gi = 0; gi < GPB; ++gi) { S[gi][kb] = __builtin_amdgcn_mfma_f32_16x16x32_bf16(kf0, qf[GPB * gh + gi][0], cinit, 0, 0, 0);
;                 S[gi][kb] = __builtin_amdgcn_mfma_f32_16x16x32_bf16(kf1, qf[GPB * gh + gi][1], S[gi][kb], 0, 0, 0); } }
;         bf16x8 pf[GPB][2];
; #pragma unroll
;         for (int gi = 0; gi < GPB; ++gi) {
;             if (MASK) {
; #pragma unroll
;                 for (int kb = 0; kb < 4; ++kb)
; #pragma unroll
;                     for (int i = 0; i < 4; ++i) { const int rel = rel0 + 16 * kb + 4 * g + i; S[gi][kb][i] = ((unsigned)(rel + 128) > 256u) ? NEGBIG : S[gi][kb][i]; }
;             }
;             ls[GPB * gh + gi] += exp_step<4>(S[gi]);
;             pf[gi][0] = pack8(S[gi][0], S[gi][1]); pf[gi][1] = pack8(S[gi][2], S[gi][3]);
;         }
; #pragma unroll
;         for (int kc = 0; kc < 2; ++kc)
; #pragma unroll
;             for (int db = 0; db < 4; ++db) {
;                 const LAS unsigned char* va = vrow + ((db ^ swz) << 5) + (32 * kc) * 128;
;                 const bf16x8 vf = cat8(vtr(va), vtr(va + 16 * 128));
; #pragma unroll
;                 for (int gi = 0; gi < GPB; ++gi) O[GPB * gh + gi][db] = __builtin_amdgcn_mfma_f32_16x16x32_bf16(vf, pf[gi][kc], O[GPB * gh + gi][db], 0, 0, 0);
;             }
;         if (SB == 1) __builtin_amdgcn_sched_barrier(0); else if (SB == 2) __builtin_amdgcn_sched_barrier(0x108);
;     }
; }
; __device__ __forceinline__ void swa_phase(LAS unsigned char* lds, const bf16_t* Q, const bf16_t* K, const bf16_t* V, bf16_t* Ob, const float* sink, float negb) {
;     ...
;         for (int t = 0; t < 4; ++t) {
	v_mfma_f32_16x16x32_bf16 v[136:139], v[104:107], v[20:23], v[0:3]
	v_exp_f32_e32 v244, v244
	v_exp_f32_e32 v245, v245
	v_mfma_f32_16x16x32_bf16 v[140:143], v[112:115], v[20:23], v[0:3]
	v_exp_f32_e32 v246, v246
	v_add_f32_e32 v144, v244, v245
	v_mfma_f32_16x16x32_bf16 v[136:139], v[108:111], v[24:27], v[136:139]
	v_exp_f32_e32 v247, v247
	v_add_f32_e32 v144, v144, v246
	v_mfma_f32_16x16x32_bf16 v[140:143], v[116:119], v[24:27], v[140:143]
	v_exp_f32_e32 v248, v248
	v_add_f32_e32 v144, v144, v247
	v_mfma_f32_16x16x32_bf16 v[64:67], v[160:163], v[176:179], v[64:67]
	v_exp_f32_e32 v249, v249
	v_add_f32_e32 v144, v144, v248
	v_mfma_f32_16x16x32_bf16 v[60:63], v[164:167], v[176:179], v[60:63]
	v_exp_f32_e32 v250, v250
	v_add_f32_e32 v144, v144, v249
	v_cvt_pk_bf16_f32 v244, v244, v245
	v_mfma_f32_16x16x32_bf16 v[56:59], v[168:171], v[176:179], v[56:59]
	v_exp_f32_e32 v251, v251
	v_add_f32_e32 v144, v144, v250
	v_cvt_pk_bf16_f32 v245, v246, v247
	v_mfma_f32_16x16x32_bf16 v[52:55], v[172:175], v[176:179], v[52:55]
	v_cvt_pk_bf16_f32 v246, v248, v249
	v_cvt_pk_bf16_f32 v247, v250, v251
	v_add_f32_e32 v144, v144, v251
	v_add_f32_e32 v130, v130, v144
	v_mfma_f32_16x16x32_bf16 v[176:179], v[104:107], v[28:31], v[0:3]
	v_exp_f32_e32 v136, v136
	v_exp_f32_e32 v137, v137
	v_mfma_f32_16x16x32_bf16 v[232:235], v[112:115], v[28:31], v[0:3]
	v_exp_f32_e32 v138, v138
	v_add_f32_e32 v144, v136, v137
	v_mfma_f32_16x16x32_bf16 v[176:179], v[108:111], v[32:35], v[176:179]
	v_exp_f32_e32 v139, v139
	v_add_f32_e32 v144, v144, v138
	v_mfma_f32_16x16x32_bf16 v[232:235], v[116:119], v[32:35], v[232:235]
	v_exp_f32_e32 v140, v140
	v_add_f32_e32 v144, v144, v139
	v_mfma_f32_16x16x32_bf16 v[48:51], v[160:163], v[244:247], v[48:51]
	v_exp_f32_e32 v141, v141
	v_add_f32_e32 v144, v144, v140
	v_mfma_f32_16x16x32_bf16 v[44:47], v[164:167], v[244:247], v[44:47]
	v_exp_f32_e32 v142, v142
	v_add_f32_e32 v144, v144, v141
	v_cvt_pk_bf16_f32 v136, v136, v137
	v_mfma_f32_16x16x32_bf16 v[40:43], v[168:171], v[244:247], v[40:43]
	v_exp_f32_e32 v143, v143
	v_add_f32_e32 v144, v144, v142
	v_cvt_pk_bf16_f32 v137, v138, v139
	v_mfma_f32_16x16x32_bf16 v[36:39], v[172:175], v[244:247], v[36:39]
	v_cvt_pk_bf16_f32 v138, v140, v141
	v_cvt_pk_bf16_f32 v139, v142, v143
	v_add_f32_e32 v144, v144, v143
	v_add_f32_e32 v129, v129, v144
	v_mfma_f32_16x16x32_bf16 v[72:75], v[160:163], v[136:139], v[72:75]
	v_exp_f32_e32 v176, v176
	v_exp_f32_e32 v177, v177
	v_exp_f32_e32 v178, v178
	v_add_f32_e32 v144, v176, v177
	v_mfma_f32_16x16x32_bf16 v[84:87], v[164:167], v[136:139], v[84:87]
	v_exp_f32_e32 v179, v179
	v_add_f32_e32 v144, v144, v178
	v_exp_f32_e32 v232, v232
	v_add_f32_e32 v144, v144, v179
	v_mfma_f32_16x16x32_bf16 v[88:91], v[168:171], v[136:139], v[88:91]
	v_exp_f32_e32 v233, v233
	v_add_f32_e32 v144, v144, v232
	v_exp_f32_e32 v234, v234
	v_add_f32_e32 v144, v144, v233
	v_cvt_pk_bf16_f32 v176, v176, v177
	v_mfma_f32_16x16x32_bf16 v[96:99], v[172:175], v[136:139], v[96:99]
	v_exp_f32_e32 v235, v235
	v_add_f32_e32 v144, v144, v234
	v_cvt_pk_bf16_f32 v177, v178, v179
	v_cvt_pk_bf16_f32 v178, v232, v233
	v_cvt_pk_bf16_f32 v179, v234, v235
	v_add_f32_e32 v144, v144, v235
	v_add_f32_e32 v128, v128, v144
	v_mfma_f32_16x16x32_bf16 v[68:71], v[160:163], v[176:179], v[68:71]
	v_mfma_f32_16x16x32_bf16 v[76:79], v[164:167], v[176:179], v[76:79]
	v_mfma_f32_16x16x32_bf16 v[80:83], v[168:171], v[176:179], v[80:83]
	v_mfma_f32_16x16x32_bf16 v[92:95], v[172:175], v[176:179], v[92:95]
	s_waitcnt vmcnt(4)
	s_barrier
	s_cmp_lt_u32 s6, s46
	s_cselect_b32 s11, s8, 0
	s_cselect_b32 s10, s7, s82
	s_lshl_b64 s[10:11], s[10:11], 9
	s_add_u32 s12, s67, s10
	s_addc_u32 s13, s4, s11
	s_add_u32 s10, s5, s10
	s_addc_u32 s11, s58, s11
	s_add_i32 s9, s40, s1
	s_mov_b32 s15, m0
	s_mov_b32 m0, s9
	s_nop 0
	global_load_lds_dwordx4 v212, s[12:13]
	s_mov_b32 m0, s15
	s_add_i32 s14, s9, 0x2000
	s_mov_b32 s9, m0
	s_mov_b32 m0, s14
	s_nop 0
	global_load_lds_dwordx4 v213, s[10:11]
	s_mov_b32 m0, s9
	s_add_i32 s34, s1, 0x4000
	v_add_u32_e32 v100, s34, v191
	v_add3_u32 v135, s34, v203, v198
	v_add_u32_e32 v102, v100, v193
	v_add_u32_e32 v100, v100, v192
	ds_read_b128 v[160:163], v100
	ds_read_b128 v[164:167], v102
	ds_read_b128 v[168:171], v100 offset:2048
	ds_read_b128 v[172:175], v102 offset:2048
	ds_read_b128 v[104:107], v100 offset:4096
	ds_read_b128 v[108:111], v102 offset:4096
	ds_read_b128 v[112:115], v100 offset:6144
	ds_read_b128 v[116:119], v102 offset:6144
	v_add_u32_e32 v103, v135, v199
	v_add_u32_e32 v133, v135, v200
	v_add_u32_e32 v134, v135, v201
	v_add_u32_e32 v135, v135, v202
	s_waitcnt lgkmcnt(4)
	v_mfma_f32_16x16x32_bf16 v[136:139], v[160:163], v[4:7], v[0:3]
	v_mfma_f32_16x16x32_bf16 v[140:143], v[168:171], v[4:7], v[0:3]
	v_mfma_f32_16x16x32_bf16 v[136:139], v[164:167], v[12:15], v[136:139]
	v_mfma_f32_16x16x32_bf16 v[140:143], v[172:175], v[12:15], v[140:143]
	ds_read_b64_tr_b16 v[216:217], v103 offset:8192
	ds_read_b64_tr_b16 v[218:219], v103 offset:10240
	ds_read_b64_tr_b16 v[220:221], v133 offset:8192
	ds_read_b64_tr_b16 v[222:223], v133 offset:10240
	ds_read_b64_tr_b16 v[224:225], v134 offset:8192
	ds_read_b64_tr_b16 v[226:227], v134 offset:10240
	ds_read_b64_tr_b16 v[228:229], v135 offset:8192
	ds_read_b64_tr_b16 v[230:231], v135 offset:10240
	v_mfma_f32_16x16x32_bf16 v[176:179], v[160:163], v[8:11], v[0:3]
	v_exp_f32_e32 v136, v136
	v_exp_f32_e32 v137, v137
	v_exp_f32_e32 v138, v138
	v_add_f32_e32 v144, v136, v137
	v_mfma_f32_16x16x32_bf16 v[232:235], v[168:171], v[8:11], v[0:3]
	v_exp_f32_e32 v139, v139
	v_add_f32_e32 v144, v144, v138
	v_exp_f32_e32 v140, v140
	v_add_f32_e32 v144, v144, v139
	v_mfma_f32_16x16x32_bf16 v[176:179], v[164:167], v[16:19], v[176:179]
	v_exp_f32_e32 v141, v141
	v_add_f32_e32 v144, v144, v140
	v_exp_f32_e32 v142, v142
	v_add_f32_e32 v144, v144, v141
	v_cvt_pk_bf16_f32 v136, v136, v137
	v_mfma_f32_16x16x32_bf16 v[232:235], v[172:175], v[16:19], v[232:235]
	v_exp_f32_e32 v143, v143
	v_add_f32_e32 v144, v144, v142
	v_cvt_pk_bf16_f32 v137, v138, v139
	v_cvt_pk_bf16_f32 v138, v140, v141
	v_cvt_pk_bf16_f32 v139, v142, v143
	v_add_f32_e32 v144, v144, v143
	v_add_f32_e32 v131, v131, v144
	s_waitcnt lgkmcnt(0)
; #define LAS __attribute__((address_space(3)))
; __device__ __forceinline__ s16x4 vtr(const LAS unsigned char* p) { return __builtin_bit_cast(s16x4, __builtin_amdgcn_ds_read_tr16_b64_v4i16((LAS v4i16_t*)p)); }
;     const int l15 = lane & 15, g = lane >> 4, q4 = l15 >> 2;
;     const LAS unsigned char* kb0 = Kt + l15 * 128;
;     const int kx0 = ((g) ^ (l15 & 7)) << 4, kx1 = ((4 + g) ^ (l15 & 7)) << 4;
;     const LAS unsigned char* vrow = Vt + (4 * g + q4) * 128 + (lane & 3) * 8;
;     const int swz = (2 * (g & 1) + (q4 >> 1)) & 3;
;     const f32x4 cinit = (f32x4){negb, negb, negb, negb};
; #pragma unroll
;     for (int gh = 0; gh < 4 / GPB; ++gh) {
;         f32x4 S[GPB][4];
; #pragma unroll
;         for (int kb = 0; kb < 4; ++kb) {
;             const bf16x8 kf0 = *(const LAS bf16x8*)(kb0 + (16 * kb) * 128 + kx0), kf1 = *(const LAS bf16x8*)(kb0 + (16 * kb) * 128 + kx1);
; #pragma unroll
;             for (int gi = 0; gi < GPB; ++gi) { S[gi][kb] = __builtin_amdgcn_mfma_f32_16x16x32_bf16(kf0, qf[GPB * gh + gi][0], cinit, 0, 0, 0);
;                 S[gi][kb] = __builtin_amdgcn_mfma_f32_16x16x32_bf16(kf1, qf[GPB * gh + gi][1], S[gi][kb], 0, 0, 0); } }
;         bf16x8 pf[GPB][2];
; #pragma unroll
;         for (int gi = 0; gi < GPB; ++gi) {
;             if (MASK) {
; #pragma unroll
;                 for (int kb = 0; kb < 4; ++kb)
; #pragma unroll
;                     for (int i = 0; i < 4; ++i) { const int rel = rel0 + 16 * kb + 4 * g + i; S[gi][kb][i] = ((unsigned)(rel + 128) > 256u) ? NEGBIG : S[gi][kb][i]; }
;             }
;             ls[GPB * gh + gi] += exp_step<4>(S[gi]);
;             pf[gi][0] = pack8(S[gi][0], S[gi][1]); pf[gi][1] = pack8(S[gi][2], S[gi][3]);
;         }
; #pragma unroll
;         for (int kc = 0; kc < 2; ++kc)
; #pragma unroll
;             for (int db = 0; db < 4; ++db) {
;                 const LAS unsigned char* va = vrow + ((db ^ swz) << 5) + (32 * kc) * 128;
;                 const bf16x8 vf = cat8(vtr(va), vtr(va + 16 * 128));
; #pragma unroll
;                 for (int gi = 0; gi < GPB; ++gi) O[GPB * gh + gi][db] = __builtin_amdgcn_mfma_f32_16x16x32_bf16(vf, pf[gi][kc], O[GPB * gh + gi][db], 0, 0, 0);
;             }
;         if (SB == 1) __builtin_amdgcn_sched_barrier(0); else if (SB == 2) __builtin_amdgcn_sched_barrier(0x108);
;     }
; }
	v_mfma_f32_16x16x32_bf16 v[244:247], v[160:163], v[20:23], v[0:3]
	v_exp_f32_e32 v176, v176
	v_exp_f32_e32 v177, v177
	v_mfma_f32_16x16x32_bf16 v[248:251], v[168:171], v[20:23], v[0:3]
	v_exp_f32_e32 v178, v178
	v_add_f32_e32 v144, v176, v177
	v_mfma_f32_16x16x32_bf16 v[244:247], v[164:167], v[24:27], v[244:247]
	v_exp_f32_e32 v179, v179
	v_add_f32_e32 v144, v144, v178
	v_mfma_f32_16x16x32_bf16 v[248:251], v[172:175], v[24:27], v[248:251]
	v_exp_f32_e32 v232, v232
	v_add_f32_e32 v144, v144, v179
	v_mfma_f32_16x16x32_bf16 v[64:67], v[216:219], v[136:139], v[64:67]
	v_exp_f32_e32 v233, v233
	v_add_f32_e32 v144, v144, v232
	v_mfma_f32_16x16x32_bf16 v[60:63], v[220:223], v[136:139], v[60:63]
	v_exp_f32_e32 v234, v234
	v_add_f32_e32 v144, v144, v233
	v_cvt_pk_bf16_f32 v176, v176, v177
	v_mfma_f32_16x16x32_bf16 v[56:59], v[224:227], v[136:139], v[56:59]
	v_exp_f32_e32 v235, v235
	v_add_f32_e32 v144, v144, v234
	v_cvt_pk_bf16_f32 v177, v178, v179
	v_mfma_f32_16x16x32_bf16 v[52:55], v[228:231], v[136:139], v[52:55]
	v_cvt_pk_bf16_f32 v178, v232, v233
	v_cvt_pk_bf16_f32 v179, v234, v235
	v_add_f32_e32 v144, v144, v235
	v_add_f32_e32 v130, v130, v144
	v_mfma_f32_16x16x32_bf16 v[136:139], v[160:163], v[28:31], v[0:3]
	v_exp_f32_e32 v244, v244
	v_exp_f32_e32 v245, v245
	v_mfma_f32_16x16x32_bf16 v[140:143], v[168:171], v[28:31], v[0:3]
	v_exp_f32_e32 v246, v246
	v_add_f32_e32 v144, v244, v245
	v_mfma_f32_16x16x32_bf16 v[136:139], v[164:167], v[32:35], v[136:139]
	v_exp_f32_e32 v247, v247
	v_add_f32_e32 v144, v144, v246
	v_mfma_f32_16x16x32_bf16 v[140:143], v[172:175], v[32:35], v[140:143]
	v_exp_f32_e32 v248, v248
	v_add_f32_e32 v144, v144, v247
	v_mfma_f32_16x16x32_bf16 v[48:51], v[216:219], v[176:179], v[48:51]
	v_exp_f32_e32 v249, v249
	v_add_f32_e32 v144, v144, v248
	v_mfma_f32_16x16x32_bf16 v[44:47], v[220:223], v[176:179], v[44:47]
	v_exp_f32_e32 v250, v250
	v_add_f32_e32 v144, v144, v249
	v_cvt_pk_bf16_f32 v244, v244, v245
	v_mfma_f32_16x16x32_bf16 v[40:43], v[224:227], v[176:179], v[40:43]
	v_exp_f32_e32 v251, v251
	v_add_f32_e32 v144, v144, v250
	v_cvt_pk_bf16_f32 v245, v246, v247
	v_mfma_f32_16x16x32_bf16 v[36:39], v[228:231], v[176:179], v[36:39]
	v_cvt_pk_bf16_f32 v246, v248, v249
	v_cvt_pk_bf16_f32 v247, v250, v251
	v_add_f32_e32 v144, v144, v251
	v_add_f32_e32 v129, v129, v144
	ds_read_b64_tr_b16 v[160:161], v103 offset:12288
	ds_read_b64_tr_b16 v[162:163], v103 offset:14336
	ds_read_b64_tr_b16 v[164:165], v133 offset:12288
	ds_read_b64_tr_b16 v[166:167], v133 offset:14336
	ds_read_b64_tr_b16 v[168:169], v134 offset:12288
	ds_read_b64_tr_b16 v[170:171], v134 offset:14336
	ds_read_b64_tr_b16 v[172:173], v135 offset:12288
	ds_read_b64_tr_b16 v[174:175], v135 offset:14336
	v_mfma_f32_16x16x32_bf16 v[176:179], v[104:107], v[4:7], v[0:3]
	v_exp_f32_e32 v136, v136
	v_exp_f32_e32 v137, v137
	v_mfma_f32_16x16x32_bf16 v[232:235], v[112:115], v[4:7], v[0:3]
	v_exp_f32_e32 v138, v138
	v_add_f32_e32 v144, v136, v137
	v_mfma_f32_16x16x32_bf16 v[176:179], v[108:111], v[12:15], v[176:179]
	v_exp_f32_e32 v139, v139
	v_add_f32_e32 v144, v144, v138
	v_mfma_f32_16x16x32_bf16 v[232:235], v[116:119], v[12:15], v[232:235]
	v_exp_f32_e32 v140, v140
	v_add_f32_e32 v144, v144, v139
	v_mfma_f32_16x16x32_bf16 v[72:75], v[216:219], v[244:247], v[72:75]
	v_exp_f32_e32 v141, v141
	v_add_f32_e32 v144, v144, v140
	v_mfma_f32_16x16x32_bf16 v[84:87], v[220:223], v[244:247], v[84:87]
	v_exp_f32_e32 v142, v142
	v_add_f32_e32 v144, v144, v141
	v_cvt_pk_bf16_f32 v136, v136, v137
	v_mfma_f32_16x16x32_bf16 v[88:91], v[224:227], v[244:247], v[88:91]
	v_exp_f32_e32 v143, v143
	v_add_f32_e32 v144, v144, v142
	v_cvt_pk_bf16_f32 v137, v138, v139
	v_mfma_f32_16x16x32_bf16 v[96:99], v[228:231], v[244:247], v[96:99]
	v_cvt_pk_bf16_f32 v138, v140, v141
	v_cvt_pk_bf16_f32 v139, v142, v143
	v_add_f32_e32 v144, v144, v143
	v_add_f32_e32 v128, v128, v144
	v_mfma_f32_16x16x32_bf16 v[244:247], v[104:107], v[8:11], v[0:3]
	v_exp_f32_e32 v176, v176
	v_exp_f32_e32 v177, v177
	v_mfma_f32_16x16x32_bf16 v[248:251], v[112:115], v[8:11], v[0:3]
	v_exp_f32_e32 v178, v178
	v_add_f32_e32 v144, v176, v177
	v_mfma_f32_16x16x32_bf16 v[244:247], v[108:111], v[16:19], v[244:247]
	v_exp_f32_e32 v179, v179
	v_add_f32_e32 v144, v144, v178
	v_mfma_f32_16x16x32_bf16 v[248:251], v[116:119], v[16:19], v[248:251]
	v_exp_f32_e32 v232, v232
	v_add_f32_e32 v144, v144, v179
	v_mfma_f32_16x16x32_bf16 v[68:71], v[216:219], v[136:139], v[68:71]
	v_exp_f32_e32 v233, v233
	v_add_f32_e32 v144, v144, v232
	v_mfma_f32_16x16x32_bf16 v[76:79], v[220:223], v[136:139], v[76:79]
	v_exp_f32_e32 v234, v234
	v_add_f32_e32 v144, v144, v233
	v_cvt_pk_bf16_f32 v176, v176, v177
	v_mfma_f32_16x16x32_bf16 v[80:83], v[224:227], v[136:139], v[80:83]
	v_exp_f32_e32 v235, v235
	v_add_f32_e32 v144, v144, v234
	v_cvt_pk_bf16_f32 v177, v178, v179
	v_mfma_f32_16x16x32_bf16 v[92:95], v[228:231], v[136:139], v[92:95]
	v_cvt_pk_bf16_f32 v178, v232, v233
	v_cvt_pk_bf16_f32 v179, v234, v235
	v_add_f32_e32 v144, v144, v235
	v_add_f32_e32 v131, v131, v144
	s_waitcnt lgkmcnt(0)
; #define LAS __attribute__((address_space(3)))
;     const int l15 = lane & 15, g = lane >> 4, q4 = l15 >> 2;
;     const LAS unsigned char* kb0 = Kt + l15 * 128;
;     const int kx0 = ((g) ^ (l15 & 7)) << 4, kx1 = ((4 + g) ^ (l15 & 7)) << 4;
;     const LAS unsigned char* vrow = Vt + (4 * g + q4) * 128 + (lane & 3) * 8;
;     const int swz = (2 * (g & 1) + (q4 >> 1)) & 3;
;     const f32x4 cinit = (f32x4){negb, negb, negb, negb};
; #pragma unroll
;     for (int gh = 0; gh < 4 / GPB; ++gh) {
;         f32x4 S[GPB][4];
; #pragma unroll
;         for (int kb = 0; kb < 4; ++kb) {
;             const bf16x8 kf0 = *(const LAS bf16x8*)(kb0 + (16 * kb) * 128 + kx0), kf1 = *(const LAS bf16x8*)(kb0 + (16 * kb) * 128 + kx1);
; #pragma unroll
;             for (int gi = 0; gi < GPB; ++gi) { S[gi][kb] = __builtin_amdgcn_mfma_f32_16x16x32_bf16(kf0, qf[GPB * gh + gi][0], cinit, 0, 0, 0);
;                 S[gi][kb] = __builtin_amdgcn_mfma_f32_16x16x32_bf16(kf1, qf[GPB * gh + gi][1], S[gi][kb], 0, 0, 0); } }
;         bf16x8 pf[GPB][2];
; #pragma unroll
;         for (int gi = 0; gi < GPB; ++gi) {
;             if (MASK) {
; #pragma unroll
;                 for (int kb = 0; kb < 4; ++kb)
; #pragma unroll
;                     for (int i = 0; i < 4; ++i) { const int rel = rel0 + 16 * kb + 4 * g + i; S[gi][kb][i] = ((unsigned)(rel + 128) > 256u) ? NEGBIG : S[gi][kb][i]; }
;             }
;             ls[GPB * gh + gi] += exp_step<4>(S[gi]);
;             pf[gi][0] = pack8(S[gi][0], S[gi][1]); pf[gi][1] = pack8(S[gi][2], S[gi][3]);
;         }
; #pragma unroll
;         for (int kc = 0; kc < 2; ++kc)
; #pragma unroll
;             for (int db = 0; db < 4; ++db) {
;                 const LAS unsigned char* va = vrow + ((db ^ swz) << 5) + (32 * kc) * 128;
;                 const bf16x8 vf = cat8(vtr(va), vtr(va + 16 * 128));
; #pragma unroll
;                 for (int gi = 0; gi < GPB; ++gi) O[GPB * gh + gi][db] = __builtin_amdgcn_mfma_f32_16x16x32_bf16(vf, pf[gi][kc], O[GPB * gh + gi][db], 0, 0, 0);
;             }
;         if (SB == 1) __builtin_amdgcn_sched_barrier(0); else if (SB == 2) __builtin_amdgcn_sched_barrier(0x108);
;     }
; }
; __device__ __forceinline__ void swa_phase(LAS unsigned char* lds, const bf16_t* Q, const bf16_t* K, const bf16_t* V, bf16_t* Ob, const float* sink, float negb) {
;     ...
;         for (int t = 0; t < 4; ++t) {
	v_mfma_f32_16x16x32_bf16 v[136:139], v[104:107], v[20:23], v[0:3]
	v_exp_f32_e32 v244, v244
	v_exp_f32_e32 v245, v245
	v_mfma_f32_16x16x32_bf16 v[140:143], v[112:115], v[20:23], v[0:3]
	v_exp_f32_e32 v246, v246
	v_add_f32_e32 v144, v244, v245
	v_mfma_f32_16x16x32_bf16 v[136:139], v[108:111], v[24:27], v[136:139]
	v_exp_f32_e32 v247, v247
	v_add_f32_e32 v144, v144, v246
	v_mfma_f32_16x16x32_bf16 v[140:143], v[116:119], v[24:27], v[140:143]
	v_exp_f32_e32 v248, v248
	v_add_f32_e32 v144, v144, v247
	v_mfma_f32_16x16x32_bf16 v[64:67], v[160:163], v[176:179], v[64:67]
	v_exp_f32_e32 v249, v249
	v_add_f32_e32 v144, v144, v248
	v_mfma_f32_16x16x32_bf16 v[60:63], v[164:167], v[176:179], v[60:63]
	v_exp_f32_e32 v250, v250
	v_add_f32_e32 v144, v144, v249
	v_cvt_pk_bf16_f32 v244, v244, v245
	v_mfma_f32_16x16x32_bf16 v[56:59], v[168:171], v[176:179], v[56:59]
	v_exp_f32_e32 v251, v251
	v_add_f32_e32 v144, v144, v250
	v_cvt_pk_bf16_f32 v245, v246, v247
	v_mfma_f32_16x16x32_bf16 v[52:55], v[172:175], v[176:179], v[52:55]
	v_cvt_pk_bf16_f32 v246, v248, v249
	v_cvt_pk_bf16_f32 v247, v250, v251
	v_add_f32_e32 v144, v144, v251
	v_add_f32_e32 v130, v130, v144
	v_mfma_f32_16x16x32_bf16 v[176:179], v[104:107], v[28:31], v[0:3]
	v_exp_f32_e32 v136, v136
	v_exp_f32_e32 v137, v137
	v_mfma_f32_16x16x32_bf16 v[232:235], v[112:115], v[28:31], v[0:3]
	v_exp_f32_e32 v138, v138
	v_add_f32_e32 v144, v136, v137
	v_mfma_f32_16x16x32_bf16 v[176:179], v[108:111], v[32:35], v[176:179]
	v_exp_f32_e32 v139, v139
	v_add_f32_e32 v144, v144, v138
	v_mfma_f32_16x16x32_bf16 v[232:235], v[116:119], v[32:35], v[232:235]
	v_exp_f32_e32 v140, v140
	v_add_f32_e32 v144, v144, v139
	v_mfma_f32_16x16x32_bf16 v[48:51], v[160:163], v[244:247], v[48:51]
	v_exp_f32_e32 v141, v141
	v_add_f32_e32 v144, v144, v140
	v_mfma_f32_16x16x32_bf16 v[44:47], v[164:167], v[244:247], v[44:47]
	v_exp_f32_e32 v142, v142
	v_add_f32_e32 v144, v144, v141
	v_cvt_pk_bf16_f32 v136, v136, v137
	v_mfma_f32_16x16x32_bf16 v[40:43], v[168:171], v[244:247], v[40:43]
	v_exp_f32_e32 v143, v143
	v_add_f32_e32 v144, v144, v142
	v_cvt_pk_bf16_f32 v137, v138, v139
	v_mfma_f32_16x16x32_bf16 v[36:39], v[172:175], v[244:247], v[36:39]
	v_cvt_pk_bf16_f32 v138, v140, v141
	v_cvt_pk_bf16_f32 v139, v142, v143
	v_add_f32_e32 v144, v144, v143
	v_add_f32_e32 v129, v129, v144
	v_mfma_f32_16x16x32_bf16 v[72:75], v[160:163], v[136:139], v[72:75]
	v_exp_f32_e32 v176, v176
	v_exp_f32_e32 v177, v177
	v_exp_f32_e32 v178, v178
	v_add_f32_e32 v144, v176, v177
	v_mfma_f32_16x16x32_bf16 v[84:87], v[164:167], v[136:139], v[84:87]
	v_exp_f32_e32 v179, v179
	v_add_f32_e32 v144, v144, v178
	v_exp_f32_e32 v232, v232
	v_add_f32_e32 v144, v144, v179
	v_mfma_f32_16x16x32_bf16 v[88:91], v[168:171], v[136:139], v[88:91]
	v_exp_f32_e32 v233, v233
	v_add_f32_e32 v144, v144, v232
	v_exp_f32_e32 v234, v234
	v_add_f32_e32 v144, v144, v233
	v_cvt_pk_bf16_f32 v176, v176, v177
	v_mfma_f32_16x16x32_bf16 v[96:99], v[172:175], v[136:139], v[96:99]
	v_exp_f32_e32 v235, v235
	v_add_f32_e32 v144, v144, v234
	v_cvt_pk_bf16_f32 v177, v178, v179
	v_cvt_pk_bf16_f32 v178, v232, v233
	v_cvt_pk_bf16_f32 v179, v234, v235
	v_add_f32_e32 v144, v144, v235
	v_add_f32_e32 v128, v128, v144
	v_mfma_f32_16x16x32_bf16 v[68:71], v[160:163], v[176:179], v[68:71]
	v_mfma_f32_16x16x32_bf16 v[76:79], v[164:167], v[176:179], v[76:79]
	v_mfma_f32_16x16x32_bf16 v[80:83], v[168:171], v[176:179], v[80:83]
	v_mfma_f32_16x16x32_bf16 v[92:95], v[172:175], v[176:179], v[92:95]
	s_addk_i32 s1, 0x4000
	s_add_u32 s7, s7, 64
	s_addc_u32 s8, s8, 0
	s_add_i32 s6, s6, 1
	s_waitcnt vmcnt(4)
	s_barrier
	s_cmp_lt_u32 s6, s46
	s_cselect_b32 s11, s8, 0
	s_cselect_b32 s10, s7, s82
	s_lshl_b64 s[10:11], s[10:11], 9
	s_add_u32 s12, s67, s10
	s_addc_u32 s13, s4, s11
	s_add_u32 s10, s5, s10
	s_addc_u32 s11, s58, s11
	s_add_i32 s9, s40, s1
	s_mov_b32 s15, m0
	s_mov_b32 m0, s9
	s_nop 0
	global_load_lds_dwordx4 v212, s[12:13]
	s_mov_b32 m0, s15
	s_add_i32 s14, s9, 0x2000
	s_mov_b32 s9, m0
	s_mov_b32 m0, s14
	s_nop 0
	global_load_lds_dwordx4 v213, s[10:11]
	s_mov_b32 m0, s9
	s_add_i32 s34, s1, 0x4000
	v_add_u32_e32 v100, s34, v191
	v_add3_u32 v135, s34, v203, v198
	v_add_u32_e32 v102, v100, v193
	v_add_u32_e32 v100, v100, v192
	ds_read_b128 v[160:163], v100
	ds_read_b128 v[164:167], v102
	ds_read_b128 v[168:171], v100 offset:2048
	ds_read_b128 v[172:175], v102 offset:2048
	ds_read_b128 v[104:107], v100 offset:4096
	ds_read_b128 v[108:111], v102 offset:4096
	ds_read_b128 v[112:115], v100 offset:6144
	ds_read_b128 v[116:119], v102 offset:6144
	v_add_u32_e32 v103, v135, v199
	v_add_u32_e32 v133, v135, v200
	v_add_u32_e32 v134, v135, v201
	v_add_u32_e32 v135, v135, v202
	s_waitcnt lgkmcnt(4)
	v_mfma_f32_16x16x32_bf16 v[136:139], v[160:163], v[4:7], v[0:3]
	v_mfma_f32_16x16x32_bf16 v[140:143], v[168:171], v[4:7], v[0:3]
	v_mfma_f32_16x16x32_bf16 v[136:139], v[164:167], v[12:15], v[136:139]
	v_mfma_f32_16x16x32_bf16 v[140:143], v[172:175], v[12:15], v[140:143]
	ds_read_b64_tr_b16 v[216:217], v103 offset:8192
	ds_read_b64_tr_b16 v[218:219], v103 offset:10240
	ds_read_b64_tr_b16 v[220:221], v133 offset:8192
	ds_read_b64_tr_b16 v[222:223], v133 offset:10240
	ds_read_b64_tr_b16 v[224:225], v134 offset:8192
	ds_read_b64_tr_b16 v[226:227], v134 offset:10240
	ds_read_b64_tr_b16 v[228:229], v135 offset:8192
	ds_read_b64_tr_b16 v[230:231], v135 offset:10240
	v_mfma_f32_16x16x32_bf16 v[176:179], v[160:163], v[8:11], v[0:3]
	v_exp_f32_e32 v136, v136
	v_exp_f32_e32 v137, v137
	v_exp_f32_e32 v138, v138
	v_add_f32_e32 v144, v136, v137
	v_mfma_f32_16x16x32_bf16 v[232:235], v[168:171], v[8:11], v[0:3]
	v_exp_f32_e32 v139, v139
	v_add_f32_e32 v144, v144, v138
	v_exp_f32_e32 v140, v140
	v_add_f32_e32 v144, v144, v139
	v_mfma_f32_16x16x32_bf16 v[176:179], v[164:167], v[16:19], v[176:179]
	v_exp_f32_e32 v141, v141
	v_add_f32_e32 v144, v144, v140
	v_exp_f32_e32 v142, v142
	v_add_f32_e32 v144, v144, v141
	v_cvt_pk_bf16_f32 v136, v136, v137
	v_mfma_f32_16x16x32_bf16 v[232:235], v[172:175], v[16:19], v[232:235]
	v_exp_f32_e32 v143, v143
	v_add_f32_e32 v144, v144, v142
	v_cvt_pk_bf16_f32 v137, v138, v139
	v_cvt_pk_bf16_f32 v138, v140, v141
	v_cvt_pk_bf16_f32 v139, v142, v143
	v_add_f32_e32 v144, v144, v143
	v_add_f32_e32 v131, v131, v144
	s_waitcnt lgkmcnt(0)
; #define LAS __attribute__((address_space(3)))
; __device__ __forceinline__ s16x4 vtr(const LAS unsigned char* p) { return __builtin_bit_cast(s16x4, __builtin_amdgcn_ds_read_tr16_b64_v4i16((LAS v4i16_t*)p)); }
;     const int l15 = lane & 15, g = lane >> 4, q4 = l15 >> 2;
;     const LAS unsigned char* kb0 = Kt + l15 * 128;
;     const int kx0 = ((g) ^ (l15 & 7)) << 4, kx1 = ((4 + g) ^ (l15 & 7)) << 4;
;     const LAS unsigned char* vrow = Vt + (4 * g + q4) * 128 + (lane & 3) * 8;
;     const int swz = (2 * (g & 1) + (q4 >> 1)) & 3;
;     const f32x4 cinit = (f32x4){negb, negb, negb, negb};
; #pragma unroll
;     for (int gh = 0; gh < 4 / GPB; ++gh) {
;         f32x4 S[GPB][4];
; #pragma unroll
;         for (int kb = 0; kb < 4; ++kb) {
;             const bf16x8 kf0 = *(const LAS bf16x8*)(kb0 + (16 * kb) * 128 + kx0), kf1 = *(const LAS bf16x8*)(kb0 + (16 * kb) * 128 + kx1);
; #pragma unroll
;             for (int gi = 0; gi < GPB; ++gi) { S[gi][kb] = __builtin_amdgcn_mfma_f32_16x16x32_bf16(kf0, qf[GPB * gh + gi][0], cinit, 0, 0, 0);
;                 S[gi][kb] = __builtin_amdgcn_mfma_f32_16x16x32_bf16(kf1, qf[GPB * gh + gi][1], S[gi][kb], 0, 0, 0); } }
;         bf16x8 pf[GPB][2];
; #pragma unroll
;         for (int gi = 0; gi < GPB; ++gi) {
;             if (MASK) {
; #pragma unroll
;                 for (int kb = 0; kb < 4; ++kb)
; #pragma unroll
;                     for (int i = 0; i < 4; ++i) { const int rel = rel0 + 16 * kb + 4 * g + i; S[gi][kb][i] = ((unsigned)(rel + 128) > 256u) ? NEGBIG : S[gi][kb][i]; }
;             }
;             ls[GPB * gh + gi] += exp_step<4>(S[gi]);
;             pf[gi][0] = pack8(S[gi][0], S[gi][1]); pf[gi][1] = pack8(S[gi][2], S[gi][3]);
;         }
; #pragma unroll
;         for (int kc = 0; kc < 2; ++kc)
; #pragma unroll
;             for (int db = 0; db < 4; ++db) {
;                 const LAS unsigned char* va = vrow + ((db ^ swz) << 5) + (32 * kc) * 128;
;                 const bf16x8 vf = cat8(vtr(va), vtr(va + 16 * 128));
; #pragma unroll
;                 for (int gi = 0; gi < GPB; ++gi) O[GPB * gh + gi][db] = __builtin_amdgcn_mfma_f32_16x16x32_bf16(vf, pf[gi][kc], O[GPB * gh + gi][db], 0, 0, 0);
;             }
;         if (SB == 1) __builtin_amdgcn_sched_barrier(0); else if (SB == 2) __builtin_amdgcn_sched_barrier(0x108);
;     }
; }
	v_mfma_f32_16x16x32_bf16 v[244:247], v[160:163], v[20:23], v[0:3]
	v_exp_f32_e32 v176, v176
	v_exp_f32_e32 v177, v177
	v_mfma_f32_16x16x32_bf16 v[248:251], v[168:171], v[20:23], v[0:3]
	v_exp_f32_e32 v178, v178
	v_add_f32_e32 v144, v176, v177
	v_mfma_f32_16x16x32_bf16 v[244:247], v[164:167], v[24:27], v[244:247]
	v_exp_f32_e32 v179, v179
	v_add_f32_e32 v144, v144, v178
	v_mfma_f32_16x16x32_bf16 v[248:251], v[172:175], v[24:27], v[248:251]
	v_exp_f32_e32 v232, v232
	v_add_f32_e32 v144, v144, v179
	v_mfma_f32_16x16x32_bf16 v[64:67], v[216:219], v[136:139], v[64:67]
	v_exp_f32_e32 v233, v233
	v_add_f32_e32 v144, v144, v232
	v_mfma_f32_16x16x32_bf16 v[60:63], v[220:223], v[136:139], v[60:63]
	v_exp_f32_e32 v234, v234
	v_add_f32_e32 v144, v144, v233
	v_cvt_pk_bf16_f32 v176, v176, v177
	v_mfma_f32_16x16x32_bf16 v[56:59], v[224:227], v[136:139], v[56:59]
	v_exp_f32_e32 v235, v235
	v_add_f32_e32 v144, v144, v234
	v_cvt_pk_bf16_f32 v177, v178, v179
	v_mfma_f32_16x16x32_bf16 v[52:55], v[228:231], v[136:139], v[52:55]
	v_cvt_pk_bf16_f32 v178, v232, v233
	v_cvt_pk_bf16_f32 v179, v234, v235
	v_add_f32_e32 v144, v144, v235
	v_add_f32_e32 v130, v130, v144
	v_mfma_f32_16x16x32_bf16 v[136:139], v[160:163], v[28:31], v[0:3]
	v_exp_f32_e32 v244, v244
	v_exp_f32_e32 v245, v245
	v_mfma_f32_16x16x32_bf16 v[140:143], v[168:171], v[28:31], v[0:3]
	v_exp_f32_e32 v246, v246
	v_add_f32_e32 v144, v244, v245
	v_mfma_f32_16x16x32_bf16 v[136:139], v[164:167], v[32:35], v[136:139]
	v_exp_f32_e32 v247, v247
	v_add_f32_e32 v144, v144, v246
	v_mfma_f32_16x16x32_bf16 v[140:143], v[172:175], v[32:35], v[140:143]
	v_exp_f32_e32 v248, v248
	v_add_f32_e32 v144, v144, v247
	v_mfma_f32_16x16x32_bf16 v[48:51], v[216:219], v[176:179], v[48:51]
	v_exp_f32_e32 v249, v249
	v_add_f32_e32 v144, v144, v248
	v_mfma_f32_16x16x32_bf16 v[44:47], v[220:223], v[176:179], v[44:47]
	v_exp_f32_e32 v250, v250
	v_add_f32_e32 v144, v144, v249
	v_cvt_pk_bf16_f32 v244, v244, v245
	v_mfma_f32_16x16x32_bf16 v[40:43], v[224:227], v[176:179], v[40:43]
	v_exp_f32_e32 v251, v251
	v_add_f32_e32 v144, v144, v250
	v_cvt_pk_bf16_f32 v245, v246, v247
	v_mfma_f32_16x16x32_bf16 v[36:39], v[228:231], v[176:179], v[36:39]
	v_cvt_pk_bf16_f32 v246, v248, v249
	v_cvt_pk_bf16_f32 v247, v250, v251
	v_add_f32_e32 v144, v144, v251
	v_add_f32_e32 v129, v129, v144
	ds_read_b64_tr_b16 v[160:161], v103 offset:12288
	ds_read_b64_tr_b16 v[162:163], v103 offset:14336
	ds_read_b64_tr_b16 v[164:165], v133 offset:12288
	ds_read_b64_tr_b16 v[166:167], v133 offset:14336
	ds_read_b64_tr_b16 v[168:169], v134 offset:12288
	ds_read_b64_tr_b16 v[170:171], v134 offset:14336
	ds_read_b64_tr_b16 v[172:173], v135 offset:12288
	ds_read_b64_tr_b16 v[174:175], v135 offset:14336
	v_mfma_f32_16x16x32_bf16 v[176:179], v[104:107], v[4:7], v[0:3]
	v_exp_f32_e32 v136, v136
	v_exp_f32_e32 v137, v137
	v_mfma_f32_16x16x32_bf16 v[232:235], v[112:115], v[4:7], v[0:3]
	v_exp_f32_e32 v138, v138
	v_add_f32_e32 v144, v136, v137
	v_mfma_f32_16x16x32_bf16 v[176:179], v[108:111], v[12:15], v[176:179]
	v_exp_f32_e32 v139, v139
	v_add_f32_e32 v144, v144, v138
	v_mfma_f32_16x16x32_bf16 v[232:235], v[116:119], v[12:15], v[232:235]
	v_exp_f32_e32 v140, v140
	v_add_f32_e32 v144, v144, v139
	v_mfma_f32_16x16x32_bf16 v[72:75], v[216:219], v[244:247], v[72:75]
	v_exp_f32_e32 v141, v141
	v_add_f32_e32 v144, v144, v140
	v_mfma_f32_16x16x32_bf16 v[84:87], v[220:223], v[244:247], v[84:87]
	v_exp_f32_e32 v142, v142
	v_add_f32_e32 v144, v144, v141
	v_cvt_pk_bf16_f32 v136, v136, v137
	v_mfma_f32_16x16x32_bf16 v[88:91], v[224:227], v[244:247], v[88:91]
	v_exp_f32_e32 v143, v143
	v_add_f32_e32 v144, v144, v142
	v_cvt_pk_bf16_f32 v137, v138, v139
	v_mfma_f32_16x16x32_bf16 v[96:99], v[228:231], v[244:247], v[96:99]
	v_cvt_pk_bf16_f32 v138, v140, v141
	v_cvt_pk_bf16_f32 v139, v142, v143
	v_add_f32_e32 v144, v144, v143
	v_add_f32_e32 v128, v128, v144
	v_mfma_f32_16x16x32_bf16 v[244:247], v[104:107], v[8:11], v[0:3]
	v_exp_f32_e32 v176, v176
	v_exp_f32_e32 v177, v177
	v_mfma_f32_16x16x32_bf16 v[248:251], v[112:115], v[8:11], v[0:3]
	v_exp_f32_e32 v178, v178
	v_add_f32_e32 v144, v176, v177
	v_mfma_f32_16x16x32_bf16 v[244:247], v[108:111], v[16:19], v[244:247]
	v_exp_f32_e32 v179, v179
	v_add_f32_e32 v144, v144, v178
	v_mfma_f32_16x16x32_bf16 v[248:251], v[116:119], v[16:19], v[248:251]
	v_exp_f32_e32 v232, v232
	v_add_f32_e32 v144, v144, v179
	v_mfma_f32_16x16x32_bf16 v[68:71], v[216:219], v[136:139], v[68:71]
	v_exp_f32_e32 v233, v233
	v_add_f32_e32 v144, v144, v232
	v_mfma_f32_16x16x32_bf16 v[76:79], v[220:223], v[136:139], v[76:79]
	v_exp_f32_e32 v234, v234
	v_add_f32_e32 v144, v144, v233
	v_cvt_pk_bf16_f32 v176, v176, v177
	v_mfma_f32_16x16x32_bf16 v[80:83], v[224:227], v[136:139], v[80:83]
	v_exp_f32_e32 v235, v235
	v_add_f32_e32 v144, v144, v234
	v_cvt_pk_bf16_f32 v177, v178, v179
	v_mfma_f32_16x16x32_bf16 v[92:95], v[228:231], v[136:139], v[92:95]
	v_cvt_pk_bf16_f32 v178, v232, v233
	v_cvt_pk_bf16_f32 v179, v234, v235
	v_add_f32_e32 v144, v144, v235
	v_add_f32_e32 v131, v131, v144
	s_waitcnt lgkmcnt(0)
; #define LAS __attribute__((address_space(3)))
;     const int l15 = lane & 15, g = lane >> 4, q4 = l15 >> 2;
;     const LAS unsigned char* kb0 = Kt + l15 * 128;
;     const int kx0 = ((g) ^ (l15 & 7)) << 4, kx1 = ((4 + g) ^ (l15 & 7)) << 4;
;     const LAS unsigned char* vrow = Vt + (4 * g + q4) * 128 + (lane & 3) * 8;
;     const int swz = (2 * (g & 1) + (q4 >> 1)) & 3;
;     const f32x4 cinit = (f32x4){negb, negb, negb, negb};
; #pragma unroll
;     for (int gh = 0; gh < 4 / GPB; ++gh) {
;         f32x4 S[GPB][4];
; #pragma unroll
;         for (int kb = 0; kb < 4; ++kb) {
;             const bf16x8 kf0 = *(const LAS bf16x8*)(kb0 + (16 * kb) * 128 + kx0), kf1 = *(const LAS bf16x8*)(kb0 + (16 * kb) * 128 + kx1);
; #pragma unroll
;             for (int gi = 0; gi < GPB; ++gi) { S[gi][kb] = __builtin_amdgcn_mfma_f32_16x16x32_bf16(kf0, qf[GPB * gh + gi][0], cinit, 0, 0, 0);
;                 S[gi][kb] = __builtin_amdgcn_mfma_f32_16x16x32_bf16(kf1, qf[GPB * gh + gi][1], S[gi][kb], 0, 0, 0); } }
;         bf16x8 pf[GPB][2];
; #pragma unroll
;         for (int gi = 0; gi < GPB; ++gi) {
;             if (MASK) {
; #pragma unroll
;                 for (int kb = 0; kb < 4; ++kb)
; #pragma unroll
;                     for (int i = 0; i < 4; ++i) { const int rel = rel0 + 16 * kb + 4 * g + i; S[gi][kb][i] = ((unsigned)(rel + 128) > 256u) ? NEGBIG : S[gi][kb][i]; }
;             }
;             ls[GPB * gh + gi] += exp_step<4>(S[gi]);
;             pf[gi][0] = pack8(S[gi][0], S[gi][1]); pf[gi][1] = pack8(S[gi][2], S[gi][3]);
;         }
; #pragma unroll
;         for (int kc = 0; kc < 2; ++kc)
; #pragma unroll
;             for (int db = 0; db < 4; ++db) {
;                 const LAS unsigned char* va = vrow + ((db ^ swz) << 5) + (32 * kc) * 128;
;                 const bf16x8 vf = cat8(vtr(va), vtr(va + 16 * 128));
; #pragma unroll
;                 for (int gi = 0; gi < GPB; ++gi) O[GPB * gh + gi][db] = __builtin_amdgcn_mfma_f32_16x16x32_bf16(vf, pf[gi][kc], O[GPB * gh + gi][db], 0, 0, 0);
;             }
;         if (SB == 1) __builtin_amdgcn_sched_barrier(0); else if (SB == 2) __builtin_amdgcn_sched_barrier(0x108);
;     }
; }
; __device__ __forceinline__ void swa_phase(LAS unsigned char* lds, const bf16_t* Q, const bf16_t* K, const bf16_t* V, bf16_t* Ob, const float* sink, float negb) {
;     ...
;         for (int t = 0; t < 4; ++t) {
	v_mfma_f32_16x16x32_bf16 v[136:139], v[104:107], v[20:23], v[0:3]
	v_exp_f32_e32 v244, v244
	v_exp_f32_e32 v245, v245
	v_mfma_f32_16x16x32_bf16 v[140:143], v[112:115], v[20:23], v[0:3]
	v_exp_f32_e32 v246, v246
	v_add_f32_e32 v144, v244, v245
	v_mfma_f32_16x16x32_bf16 v[136:139], v[108:111], v[24:27], v[136:139]
	v_exp_f32_e32 v247, v247
	v_add_f32_e32 v144, v144, v246
	v_mfma_f32_16x16x32_bf16 v[140:143], v[116:119], v[24:27], v[140:143]
	v_exp_f32_e32 v248, v248
	v_add_f32_e32 v144, v144, v247
	v_mfma_f32_16x16x32_bf16 v[64:67], v[160:163], v[176:179], v[64:67]
	v_exp_f32_e32 v249, v249
	v_add_f32_e32 v144, v144, v248
	v_mfma_f32_16x16x32_bf16 v[60:63], v[164:167], v[176:179], v[60:63]
	v_exp_f32_e32 v250, v250
	v_add_f32_e32 v144, v144, v249
	v_cvt_pk_bf16_f32 v244, v244, v245
	v_mfma_f32_16x16x32_bf16 v[56:59], v[168:171], v[176:179], v[56:59]
	v_exp_f32_e32 v251, v251
	v_add_f32_e32 v144, v144, v250
	v_cvt_pk_bf16_f32 v245, v246, v247
	v_mfma_f32_16x16x32_bf16 v[52:55], v[172:175], v[176:179], v[52:55]
	v_cvt_pk_bf16_f32 v246, v248, v249
	v_cvt_pk_bf16_f32 v247, v250, v251
	v_add_f32_e32 v144, v144, v251
	v_add_f32_e32 v130, v130, v144
	v_mfma_f32_16x16x32_bf16 v[176:179], v[104:107], v[28:31], v[0:3]
	v_exp_f32_e32 v136, v136
	v_exp_f32_e32 v137, v137
	v_mfma_f32_16x16x32_bf16 v[232:235], v[112:115], v[28:31], v[0:3]
	v_exp_f32_e32 v138, v138
	v_add_f32_e32 v144, v136, v137
	v_mfma_f32_16x16x32_bf16 v[176:179], v[108:111], v[32:35], v[176:179]
	v_exp_f32_e32 v139, v139
	v_add_f32_e32 v144, v144, v138
	v_mfma_f32_16x16x32_bf16 v[232:235], v[116:119], v[32:35], v[232:235]
	v_exp_f32_e32 v140, v140
	v_add_f32_e32 v144, v144, v139
	v_mfma_f32_16x16x32_bf16 v[48:51], v[160:163], v[244:247], v[48:51]
	v_exp_f32_e32 v141, v141
	v_add_f32_e32 v144, v144, v140
	v_mfma_f32_16x16x32_bf16 v[44:47], v[164:167], v[244:247], v[44:47]
	v_exp_f32_e32 v142, v142
	v_add_f32_e32 v144, v144, v141
	v_cvt_pk_bf16_f32 v136, v136, v137
	v_mfma_f32_16x16x32_bf16 v[40:43], v[168:171], v[244:247], v[40:43]
	v_exp_f32_e32 v143, v143
	v_add_f32_e32 v144, v144, v142
	v_cvt_pk_bf16_f32 v137, v138, v139
	v_mfma_f32_16x16x32_bf16 v[36:39], v[172:175], v[244:247], v[36:39]
	v_cvt_pk_bf16_f32 v138, v140, v141
	v_cvt_pk_bf16_f32 v139, v142, v143
	v_add_f32_e32 v144, v144, v143
	v_add_f32_e32 v129, v129, v144
	v_mfma_f32_16x16x32_bf16 v[72:75], v[160:163], v[136:139], v[72:75]
	v_exp_f32_e32 v176, v176
	v_exp_f32_e32 v177, v177
	v_exp_f32_e32 v178, v178
	v_add_f32_e32 v144, v176, v177
	v_mfma_f32_16x16x32_bf16 v[84:87], v[164:167], v[136:139], v[84:87]
	v_exp_f32_e32 v179, v179
	v_add_f32_e32 v144, v144, v178
	v_exp_f32_e32 v232, v232
	v_add_f32_e32 v144, v144, v179
	v_mfma_f32_16x16x32_bf16 v[88:91], v[168:171], v[136:139], v[88:91]
	v_exp_f32_e32 v233, v233
	v_add_f32_e32 v144, v144, v232
	v_exp_f32_e32 v234, v234
	v_add_f32_e32 v144, v144, v233
	v_cvt_pk_bf16_f32 v176, v176, v177
	v_mfma_f32_16x16x32_bf16 v[96:99], v[172:175], v[136:139], v[96:99]
	v_exp_f32_e32 v235, v235
	v_add_f32_e32 v144, v144, v234
	v_cvt_pk_bf16_f32 v177, v178, v179
	v_cvt_pk_bf16_f32 v178, v232, v233
	v_cvt_pk_bf16_f32 v179, v234, v235
	v_add_f32_e32 v144, v144, v235
	v_add_f32_e32 v128, v128, v144
	v_mfma_f32_16x16x32_bf16 v[68:71], v[160:163], v[176:179], v[68:71]
	v_mfma_f32_16x16x32_bf16 v[76:79], v[164:167], v[176:179], v[76:79]
	v_mfma_f32_16x16x32_bf16 v[80:83], v[168:171], v[176:179], v[80:83]
	v_mfma_f32_16x16x32_bf16 v[92:95], v[172:175], v[176:179], v[92:95]
	s_addk_i32 s1, 0x4000
	s_add_u32 s7, s7, 64
	s_addc_u32 s8, s8, 0
	s_add_i32 s6, s6, 1
	s_waitcnt vmcnt(4)
	s_barrier
	s_cmp_lt_u32 s6, s46
	s_cselect_b32 s11, s8, 0
	s_cselect_b32 s10, s7, s82
	s_lshl_b64 s[10:11], s[10:11], 9
	s_add_u32 s12, s67, s10
	s_addc_u32 s13, s4, s11
	s_add_u32 s10, s5, s10
	s_addc_u32 s11, s58, s11
	s_add_i32 s9, s40, s1
	s_mov_b32 s15, m0
	s_mov_b32 m0, s9
	s_nop 0
	global_load_lds_dwordx4 v212, s[12:13]
	s_mov_b32 m0, s15
	s_add_i32 s14, s9, 0x2000
	s_mov_b32 s9, m0
	s_mov_b32 m0, s14
	s_nop 0
	global_load_lds_dwordx4 v213, s[10:11]
	s_mov_b32 m0, s9
	s_add_i32 s34, s1, 0x4000
	v_add_u32_e32 v100, s34, v191
	v_add3_u32 v135, s34, v203, v198
	v_add_u32_e32 v102, v100, v193
	v_add_u32_e32 v100, v100, v192
	ds_read_b128 v[160:163], v100
	ds_read_b128 v[164:167], v102
	ds_read_b128 v[168:171], v100 offset:2048
	ds_read_b128 v[172:175], v102 offset:2048
	ds_read_b128 v[104:107], v100 offset:4096
	ds_read_b128 v[108:111], v102 offset:4096
	ds_read_b128 v[112:115], v100 offset:6144
	ds_read_b128 v[116:119], v102 offset:6144
	v_add_u32_e32 v103, v135, v199
	v_add_u32_e32 v133, v135, v200
	v_add_u32_e32 v134, v135, v201
	v_add_u32_e32 v135, v135, v202
	s_waitcnt lgkmcnt(4)
	v_mfma_f32_16x16x32_bf16 v[136:139], v[160:163], v[4:7], v[0:3]
	v_mfma_f32_16x16x32_bf16 v[140:143], v[168:171], v[4:7], v[0:3]
	v_mfma_f32_16x16x32_bf16 v[136:139], v[164:167], v[12:15], v[136:139]
	v_mfma_f32_16x16x32_bf16 v[140:143], v[172:175], v[12:15], v[140:143]
	ds_read_b64_tr_b16 v[216:217], v103 offset:8192
	ds_read_b64_tr_b16 v[218:219], v103 offset:10240
	ds_read_b64_tr_b16 v[220:221], v133 offset:8192
	ds_read_b64_tr_b16 v[222:223], v133 offset:10240
	ds_read_b64_tr_b16 v[224:225], v134 offset:8192
	ds_read_b64_tr_b16 v[226:227], v134 offset:10240
	ds_read_b64_tr_b16 v[228:229], v135 offset:8192
	ds_read_b64_tr_b16 v[230:231], v135 offset:10240
	v_mfma_f32_16x16x32_bf16 v[176:179], v[160:163], v[8:11], v[0:3]
	v_exp_f32_e32 v136, v136
	v_exp_f32_e32 v137, v137
	v_exp_f32_e32 v138, v138
	v_add_f32_e32 v144, v136, v137
	v_mfma_f32_16x16x32_bf16 v[232:235], v[168:171], v[8:11], v[0:3]
	v_exp_f32_e32 v139, v139
	v_add_f32_e32 v144, v144, v138
	v_exp_f32_e32 v140, v140
	v_add_f32_e32 v144, v144, v139
	v_mfma_f32_16x16x32_bf16 v[176:179], v[164:167], v[16:19], v[176:179]
	v_exp_f32_e32 v141, v141
	v_add_f32_e32 v144, v144, v140
	v_exp_f32_e32 v142, v142
	v_add_f32_e32 v144, v144, v141
	v_cvt_pk_bf16_f32 v136, v136, v137
	v_mfma_f32_16x16x32_bf16 v[232:235], v[172:175], v[16:19], v[232:235]
	v_exp_f32_e32 v143, v143
	v_add_f32_e32 v144, v144, v142
	v_cvt_pk_bf16_f32 v137, v138, v139
	v_cvt_pk_bf16_f32 v138, v140, v141
	v_cvt_pk_bf16_f32 v139, v142, v143
	v_add_f32_e32 v144, v144, v143
	v_add_f32_e32 v131, v131, v144
	s_waitcnt lgkmcnt(0)
; #define LAS __attribute__((address_space(3)))
; __device__ __forceinline__ s16x4 vtr(const LAS unsigned char* p) { return __builtin_bit_cast(s16x4, __builtin_amdgcn_ds_read_tr16_b64_v4i16((LAS v4i16_t*)p)); }
;     const int l15 = lane & 15, g = lane >> 4, q4 = l15 >> 2;
;     const LAS unsigned char* kb0 = Kt + l15 * 128;
;     const int kx0 = ((g) ^ (l15 & 7)) << 4, kx1 = ((4 + g) ^ (l15 & 7)) << 4;
;     const LAS unsigned char* vrow = Vt + (4 * g + q4) * 128 + (lane & 3) * 8;
;     const int swz = (2 * (g & 1) + (q4 >> 1)) & 3;
;     const f32x4 cinit = (f32x4){negb, negb, negb, negb};
; #pragma unroll
;     for (int gh = 0; gh < 4 / GPB; ++gh) {
;         f32x4 S[GPB][4];
; #pragma unroll
;         for (int kb = 0; kb < 4; ++kb) {
;             const bf16x8 kf0 = *(const LAS bf16x8*)(kb0 + (16 * kb) * 128 + kx0), kf1 = *(const LAS bf16x8*)(kb0 + (16 * kb) * 128 + kx1);
; #pragma unroll
;             for (int gi = 0; gi < GPB; ++gi) { S[gi][kb] = __builtin_amdgcn_mfma_f32_16x16x32_bf16(kf0, qf[GPB * gh + gi][0], cinit, 0, 0, 0);
;                 S[gi][kb] = __builtin_amdgcn_mfma_f32_16x16x32_bf16(kf1, qf[GPB * gh + gi][1], S[gi][kb], 0, 0, 0); } }
;         bf16x8 pf[GPB][2];
; #pragma unroll
;         for (int gi = 0; gi < GPB; ++gi) {
;             if (MASK) {
; #pragma unroll
;                 for (int kb = 0; kb < 4; ++kb)
; #pragma unroll
;                     for (int i = 0; i < 4; ++i) { const int rel = rel0 + 16 * kb + 4 * g + i; S[gi][kb][i] = ((unsigned)(rel + 128) > 256u) ? NEGBIG : S[gi][kb][i]; }
;             }
;             ls[GPB * gh + gi] += exp_step<4>(S[gi]);
;             pf[gi][0] = pack8(S[gi][0], S[gi][1]); pf[gi][1] = pack8(S[gi][2], S[gi][3]);
;         }
; #pragma unroll
;         for (int kc = 0; kc < 2; ++kc)
; #pragma unroll
;             for (int db = 0; db < 4; ++db) {
;                 const LAS unsigned char* va = vrow + ((db ^ swz) << 5) + (32 * kc) * 128;
;                 const bf16x8 vf = cat8(vtr(va), vtr(va + 16 * 128));
; #pragma unroll
;                 for (int gi = 0; gi < GPB; ++gi) O[GPB * gh + gi][db] = __builtin_amdgcn_mfma_f32_16x16x32_bf16(vf, pf[gi][kc], O[GPB * gh + gi][db], 0, 0, 0);
;             }
;         if (SB == 1) __builtin_amdgcn_sched_barrier(0); else if (SB == 2) __builtin_amdgcn_sched_barrier(0x108);
;     }
; }
	v_mfma_f32_16x16x32_bf16 v[244:247], v[160:163], v[20:23], v[0:3]
	v_exp_f32_e32 v176, v176
	v_exp_f32_e32 v177, v177
	v_mfma_f32_16x16x32_bf16 v[248:251], v[168:171], v[20:23], v[0:3]
	v_exp_f32_e32 v178, v178
	v_add_f32_e32 v144, v176, v177
	v_mfma_f32_16x16x32_bf16 v[244:247], v[164:167], v[24:27], v[244:247]
	v_exp_f32_e32 v179, v179
	v_add_f32_e32 v144, v144, v178
	v_mfma_f32_16x16x32_bf16 v[248:251], v[172:175], v[24:27], v[248:251]
	v_exp_f32_e32 v232, v232
	v_add_f32_e32 v144, v144, v179
	v_mfma_f32_16x16x32_bf16 v[64:67], v[216:219], v[136:139], v[64:67]
	v_exp_f32_e32 v233, v233
	v_add_f32_e32 v144, v144, v232
	v_mfma_f32_16x16x32_bf16 v[60:63], v[220:223], v[136:139], v[60:63]
	v_exp_f32_e32 v234, v234
	v_add_f32_e32 v144, v144, v233
	v_cvt_pk_bf16_f32 v176, v176, v177
	v_mfma_f32_16x16x32_bf16 v[56:59], v[224:227], v[136:139], v[56:59]
	v_exp_f32_e32 v235, v235
	v_add_f32_e32 v144, v144, v234
	v_cvt_pk_bf16_f32 v177, v178, v179
	v_mfma_f32_16x16x32_bf16 v[52:55], v[228:231], v[136:139], v[52:55]
	v_cvt_pk_bf16_f32 v178, v232, v233
	v_cvt_pk_bf16_f32 v179, v234, v235
	v_add_f32_e32 v144, v144, v235
	v_add_f32_e32 v130, v130, v144
	v_mfma_f32_16x16x32_bf16 v[136:139], v[160:163], v[28:31], v[0:3]
	v_exp_f32_e32 v244, v244
	v_exp_f32_e32 v245, v245
	v_mfma_f32_16x16x32_bf16 v[140:143], v[168:171], v[28:31], v[0:3]
	v_exp_f32_e32 v246, v246
	v_add_f32_e32 v144, v244, v245
	v_mfma_f32_16x16x32_bf16 v[136:139], v[164:167], v[32:35], v[136:139]
	v_exp_f32_e32 v247, v247
	v_add_f32_e32 v144, v144, v246
	v_mfma_f32_16x16x32_bf16 v[140:143], v[172:175], v[32:35], v[140:143]
	v_exp_f32_e32 v248, v248
	v_add_f32_e32 v144, v144, v247
	v_mfma_f32_16x16x32_bf16 v[48:51], v[216:219], v[176:179], v[48:51]
	v_exp_f32_e32 v249, v249
	v_add_f32_e32 v144, v144, v248
	v_mfma_f32_16x16x32_bf16 v[44:47], v[220:223], v[176:179], v[44:47]
	v_exp_f32_e32 v250, v250
	v_add_f32_e32 v144, v144, v249
	v_cvt_pk_bf16_f32 v244, v244, v245
	v_mfma_f32_16x16x32_bf16 v[40:43], v[224:227], v[176:179], v[40:43]
	v_exp_f32_e32 v251, v251
	v_add_f32_e32 v144, v144, v250
	v_cvt_pk_bf16_f32 v245, v246, v247
	v_mfma_f32_16x16x32_bf16 v[36:39], v[228:231], v[176:179], v[36:39]
	v_cvt_pk_bf16_f32 v246, v248, v249
	v_cvt_pk_bf16_f32 v247, v250, v251
	v_add_f32_e32 v144, v144, v251
	v_add_f32_e32 v129, v129, v144
	ds_read_b64_tr_b16 v[160:161], v103 offset:12288
	ds_read_b64_tr_b16 v[162:163], v103 offset:14336
	ds_read_b64_tr_b16 v[164:165], v133 offset:12288
	ds_read_b64_tr_b16 v[166:167], v133 offset:14336
	ds_read_b64_tr_b16 v[168:169], v134 offset:12288
	ds_read_b64_tr_b16 v[170:171], v134 offset:14336
	ds_read_b64_tr_b16 v[172:173], v135 offset:12288
	ds_read_b64_tr_b16 v[174:175], v135 offset:14336
	v_mfma_f32_16x16x32_bf16 v[176:179], v[104:107], v[4:7], v[0:3]
	v_exp_f32_e32 v136, v136
	v_exp_f32_e32 v137, v137
	v_mfma_f32_16x16x32_bf16 v[232:235], v[112:115], v[4:7], v[0:3]
	v_exp_f32_e32 v138, v138
	v_add_f32_e32 v144, v136, v137
	v_mfma_f32_16x16x32_bf16 v[176:179], v[108:111], v[12:15], v[176:179]
	v_exp_f32_e32 v139, v139
	v_add_f32_e32 v144, v144, v138
	v_mfma_f32_16x16x32_bf16 v[232:235], v[116:119], v[12:15], v[232:235]
	v_exp_f32_e32 v140, v140
	v_add_f32_e32 v144, v144, v139
	v_mfma_f32_16x16x32_bf16 v[72:75], v[216:219], v[244:247], v[72:75]
	v_exp_f32_e32 v141, v141
	v_add_f32_e32 v144, v144, v140
	v_mfma_f32_16x16x32_bf16 v[84:87], v[220:223], v[244:247], v[84:87]
	v_exp_f32_e32 v142, v142
	v_add_f32_e32 v144, v144, v141
	v_cvt_pk_bf16_f32 v136, v136, v137
	v_mfma_f32_16x16x32_bf16 v[88:91], v[224:227], v[244:247], v[88:91]
	v_exp_f32_e32 v143, v143
	v_add_f32_e32 v144, v144, v142
	v_cvt_pk_bf16_f32 v137, v138, v139
	v_mfma_f32_16x16x32_bf16 v[96:99], v[228:231], v[244:247], v[96:99]
	v_cvt_pk_bf16_f32 v138, v140, v141
	v_cvt_pk_bf16_f32 v139, v142, v143
	v_add_f32_e32 v144, v144, v143
	v_add_f32_e32 v128, v128, v144
	v_mfma_f32_16x16x32_bf16 v[244:247], v[104:107], v[8:11], v[0:3]
	v_exp_f32_e32 v176, v176
	v_exp_f32_e32 v177, v177
	v_mfma_f32_16x16x32_bf16 v[248:251], v[112:115], v[8:11], v[0:3]
	v_exp_f32_e32 v178, v178
	v_add_f32_e32 v144, v176, v177
	v_mfma_f32_16x16x32_bf16 v[244:247], v[108:111], v[16:19], v[244:247]
	v_exp_f32_e32 v179, v179
	v_add_f32_e32 v144, v144, v178
	v_mfma_f32_16x16x32_bf16 v[248:251], v[116:119], v[16:19], v[248:251]
	v_exp_f32_e32 v232, v232
	v_add_f32_e32 v144, v144, v179
	v_mfma_f32_16x16x32_bf16 v[68:71], v[216:219], v[136:139], v[68:71]
	v_exp_f32_e32 v233, v233
	v_add_f32_e32 v144, v144, v232
	v_mfma_f32_16x16x32_bf16 v[76:79], v[220:223], v[136:139], v[76:79]
	v_exp_f32_e32 v234, v234
	v_add_f32_e32 v144, v144, v233
	v_cvt_pk_bf16_f32 v176, v176, v177
	v_mfma_f32_16x16x32_bf16 v[80:83], v[224:227], v[136:139], v[80:83]
	v_exp_f32_e32 v235, v235
	v_add_f32_e32 v144, v144, v234
	v_cvt_pk_bf16_f32 v177, v178, v179
	v_mfma_f32_16x16x32_bf16 v[92:95], v[228:231], v[136:139], v[92:95]
	v_cvt_pk_bf16_f32 v178, v232, v233
	v_cvt_pk_bf16_f32 v179, v234, v235
	v_add_f32_e32 v144, v144, v235
	v_add_f32_e32 v131, v131, v144
	s_waitcnt lgkmcnt(0)
; #define LAS __attribute__((address_space(3)))
;     const int l15 = lane & 15, g = lane >> 4, q4 = l15 >> 2;
;     const LAS unsigned char* kb0 = Kt + l15 * 128;
;     const int kx0 = ((g) ^ (l15 & 7)) << 4, kx1 = ((4 + g) ^ (l15 & 7)) << 4;
;     const LAS unsigned char* vrow = Vt + (4 * g + q4) * 128 + (lane & 3) * 8;
;     const int swz = (2 * (g & 1) + (q4 >> 1)) & 3;
;     const f32x4 cinit = (f32x4){negb, negb, negb, negb};
; #pragma unroll
;     for (int gh = 0; gh < 4 / GPB; ++gh) {
;         f32x4 S[GPB][4];
; #pragma unroll
;         for (int kb = 0; kb < 4; ++kb) {
;             const bf16x8 kf0 = *(const LAS bf16x8*)(kb0 + (16 * kb) * 128 + kx0), kf1 = *(const LAS bf16x8*)(kb0 + (16 * kb) * 128 + kx1);
; #pragma unroll
;             for (int gi = 0; gi < GPB; ++gi) { S[gi][kb] = __builtin_amdgcn_mfma_f32_16x16x32_bf16(kf0, qf[GPB * gh + gi][0], cinit, 0, 0, 0);
;                 S[gi][kb] = __builtin_amdgcn_mfma_f32_16x16x32_bf16(kf1, qf[GPB * gh + gi][1], S[gi][kb], 0, 0, 0); } }
;         bf16x8 pf[GPB][2];
; #pragma unroll
;         for (int gi = 0; gi < GPB; ++gi) {
;             if (MASK) {
; #pragma unroll
;                 for (int kb = 0; kb < 4; ++kb)
; #pragma unroll
;                     for (int i = 0; i < 4; ++i) { const int rel = rel0 + 16 * kb + 4 * g + i; S[gi][kb][i] = ((unsigned)(rel + 128) > 256u) ? NEGBIG : S[gi][kb][i]; }
;             }
;             ls[GPB * gh + gi] += exp_step<4>(S[gi]);
;             pf[gi][0] = pack8(S[gi][0], S[gi][1]); pf[gi][1] = pack8(S[gi][2], S[gi][3]);
;         }
; #pragma unroll
;         for (int kc = 0; kc < 2; ++kc)
; #pragma unroll
;             for (int db = 0; db < 4; ++db) {
;                 const LAS unsigned char* va = vrow + ((db ^ swz) << 5) + (32 * kc) * 128;
;                 const bf16x8 vf = cat8(vtr(va), vtr(va + 16 * 128));
; #pragma unroll
;                 for (int gi = 0; gi < GPB; ++gi) O[GPB * gh + gi][db] = __builtin_amdgcn_mfma_f32_16x16x32_bf16(vf, pf[gi][kc], O[GPB * gh + gi][db], 0, 0, 0);
;             }
;         if (SB == 1) __builtin_amdgcn_sched_barrier(0); else if (SB == 2) __builtin_amdgcn_sched_barrier(0x108);
;     }
; }
; __device__ __forceinline__ void swa_phase(LAS unsigned char* lds, const bf16_t* Q, const bf16_t* K, const bf16_t* V, bf16_t* Ob, const float* sink, float negb) {
;     ...
;         for (int t = 4; t < NT; ++t) {
	v_mfma_f32_16x16x32_bf16 v[136:139], v[104:107], v[20:23], v[0:3]
	v_exp_f32_e32 v244, v244
	v_exp_f32_e32 v245, v245
	v_mfma_f32_16x16x32_bf16 v[140:143], v[112:115], v[20:23], v[0:3]
	v_exp_f32_e32 v246, v246
	v_add_f32_e32 v144, v244, v245
	v_mfma_f32_16x16x32_bf16 v[136:139], v[108:111], v[24:27], v[136:139]
	v_exp_f32_e32 v247, v247
	v_add_f32_e32 v144, v144, v246
	v_mfma_f32_16x16x32_bf16 v[140:143], v[116:119], v[24:27], v[140:143]
	v_exp_f32_e32 v248, v248
	v_add_f32_e32 v144, v144, v247
	v_mfma_f32_16x16x32_bf16 v[64:67], v[160:163], v[176:179], v[64:67]
	v_exp_f32_e32 v249, v249
	v_add_f32_e32 v144, v144, v248
	v_mfma_f32_16x16x32_bf16 v[60:63], v[164:167], v[176:179], v[60:63]
	v_exp_f32_e32 v250, v250
	v_add_f32_e32 v144, v144, v249
	v_cvt_pk_bf16_f32 v244, v244, v245
	v_mfma_f32_16x16x32_bf16 v[56:59], v[168:171], v[176:179], v[56:59]
	v_exp_f32_e32 v251, v251
	v_add_f32_e32 v144, v144, v250
	v_cvt_pk_bf16_f32 v245, v246, v247
	v_mfma_f32_16x16x32_bf16 v[52:55], v[172:175], v[176:179], v[52:55]
	v_cvt_pk_bf16_f32 v246, v248, v249
	v_cvt_pk_bf16_f32 v247, v250, v251
	v_add_f32_e32 v144, v144, v251
	v_add_f32_e32 v130, v130, v144
	v_mfma_f32_16x16x32_bf16 v[176:179], v[104:107], v[28:31], v[0:3]
	v_exp_f32_e32 v136, v136
	v_exp_f32_e32 v137, v137
	v_mfma_f32_16x16x32_bf16 v[232:235], v[112:115], v[28:31], v[0:3]
	v_exp_f32_e32 v138, v138
	v_add_f32_e32 v144, v136, v137
	v_mfma_f32_16x16x32_bf16 v[176:179], v[108:111], v[32:35], v[176:179]
	v_exp_f32_e32 v139, v139
	v_add_f32_e32 v144, v144, v138
	v_mfma_f32_16x16x32_bf16 v[232:235], v[116:119], v[32:35], v[232:235]
	v_exp_f32_e32 v140, v140
	v_add_f32_e32 v144, v144, v139
	v_mfma_f32_16x16x32_bf16 v[48:51], v[160:163], v[244:247], v[48:51]
	v_exp_f32_e32 v141, v141
	v_add_f32_e32 v144, v144, v140
	v_mfma_f32_16x16x32_bf16 v[44:47], v[164:167], v[244:247], v[44:47]
	v_exp_f32_e32 v142, v142
	v_add_f32_e32 v144, v144, v141
	v_cvt_pk_bf16_f32 v136, v136, v137
	v_mfma_f32_16x16x32_bf16 v[40:43], v[168:171], v[244:247], v[40:43]
	v_exp_f32_e32 v143, v143
	v_add_f32_e32 v144, v144, v142
	v_cvt_pk_bf16_f32 v137, v138, v139
	v_mfma_f32_16x16x32_bf16 v[36:39], v[172:175], v[244:247], v[36:39]
	v_cvt_pk_bf16_f32 v138, v140, v141
	v_cvt_pk_bf16_f32 v139, v142, v143
	v_add_f32_e32 v144, v144, v143
	v_add_f32_e32 v129, v129, v144
	v_mfma_f32_16x16x32_bf16 v[72:75], v[160:163], v[136:139], v[72:75]
	v_exp_f32_e32 v176, v176
	v_exp_f32_e32 v177, v177
	v_exp_f32_e32 v178, v178
	v_add_f32_e32 v144, v176, v177
	v_mfma_f32_16x16x32_bf16 v[84:87], v[164:167], v[136:139], v[84:87]
	v_exp_f32_e32 v179, v179
	v_add_f32_e32 v144, v144, v178
	v_exp_f32_e32 v232, v232
	v_add_f32_e32 v144, v144, v179
	v_mfma_f32_16x16x32_bf16 v[88:91], v[168:171], v[136:139], v[88:91]
	v_exp_f32_e32 v233, v233
	v_add_f32_e32 v144, v144, v232
	v_exp_f32_e32 v234, v234
	v_add_f32_e32 v144, v144, v233
	v_cvt_pk_bf16_f32 v176, v176, v177
	v_mfma_f32_16x16x32_bf16 v[96:99], v[172:175], v[136:139], v[96:99]
	v_exp_f32_e32 v235, v235
	v_add_f32_e32 v144, v144, v234
	v_cvt_pk_bf16_f32 v177, v178, v179
	v_cvt_pk_bf16_f32 v178, v232, v233
	v_cvt_pk_bf16_f32 v179, v234, v235
	v_add_f32_e32 v144, v144, v235
	v_add_f32_e32 v128, v128, v144
	v_mfma_f32_16x16x32_bf16 v[68:71], v[160:163], v[176:179], v[68:71]
	v_mfma_f32_16x16x32_bf16 v[76:79], v[164:167], v[176:179], v[76:79]
	v_mfma_f32_16x16x32_bf16 v[80:83], v[168:171], v[176:179], v[80:83]
	v_mfma_f32_16x16x32_bf16 v[92:95], v[172:175], v[176:179], v[92:95]
	s_addk_i32 s1, 0x4000
	s_add_u32 s7, s7, 64
	s_addc_u32 s8, s8, 0
	s_add_i32 s6, s6, 1
	s_waitcnt vmcnt(4)
	s_barrier
	s_add_i32 s48, s0, 0xffffff80
	s_add_i32 s49, s0, 0x8f
	s_add_i32 s50, s45, 0xffffffbf
	s_mov_b32 s51, 0
	s_mov_b32 s52, 0x10000
	v_mov_b32_e32 v132, v211
	s_branch .LBB0_355

; #define LAS __attribute__((address_space(3)))
;     const int l15 = lane & 15, g = lane >> 4, q4 = l15 >> 2;
;     const LAS unsigned char* kb0 = Kt + l15 * 128;
;     const int kx0 = ((g) ^ (l15 & 7)) << 4, kx1 = ((4 + g) ^ (l15 & 7)) << 4;
;     const LAS unsigned char* vrow = Vt + (4 * g + q4) * 128 + (lane & 3) * 8;
;     const int swz = (2 * (g & 1) + (q4 >> 1)) & 3;
;     const f32x4 cinit = (f32x4){negb, negb, negb, negb};
; #pragma unroll
;     for (int gh = 0; gh < 4 / GPB; ++gh) {
;         f32x4 S[GPB][4];
; #pragma unroll
;         for (int kb = 0; kb < 4; ++kb) {
;             const bf16x8 kf0 = *(const LAS bf16x8*)(kb0 + (16 * kb) * 128 + kx0), kf1 = *(const LAS bf16x8*)(kb0 + (16 * kb) * 128 + kx1);
; #pragma unroll
;             for (int gi = 0; gi < GPB; ++gi) { S[gi][kb] = __builtin_amdgcn_mfma_f32_16x16x32_bf16(kf0, qf[GPB * gh + gi][0], cinit, 0, 0, 0);
;                 S[gi][kb] = __builtin_amdgcn_mfma_f32_16x16x32_bf16(kf1, qf[GPB * gh + gi][1], S[gi][kb], 0, 0, 0); } }
; __device__ __forceinline__ void swa_phase(LAS unsigned char* lds, const bf16_t* Q, const bf16_t* K, const bf16_t* V, bf16_t* Ob, const float* sink, float negb) {
;     ...
;         for (int t = 4; t < NT; ++t) {
;             dma_tile<1>(lds + ((t + 3) & 3) * SW_BUF, K, V, SW_ROW0(t + 3), 256, dl, w);
;             const LAS unsigned char* buf = lds + (t & 3) * SW_BUF;
;             const int start = 128 * tb - 128 + 64 * (i_lo + t - 4);
;             if (start + 63 >= tq - 128 && start <= tq + 15 + 128)
;                 full_tile<1, 2, 2>(O, ls, qf, negb, buf, buf + 8192, lane, start - (tq + l15));
.LBB0_355:
	s_add_i32 s1, s52, 0xc000
	s_and_b32 s1, s1, 0xc000
	s_add_i32 s9, s47, s45
	s_add_i32 s8, s1, 0
	s_add_i32 s1, s9, 64
	s_add_i32 s0, s51, 7
	s_ashr_i32 s6, s1, 31
	s_add_u32 s7, s1, s43
	s_addc_u32 s1, s6, 0
	s_cmp_lt_u32 s0, s46
	s_cselect_b32 s1, s1, 0
	s_cselect_b32 s0, s7, s82
	s_lshl_b64 s[0:1], s[0:1], 9
	s_add_u32 s6, s67, s0
	s_addc_u32 s7, s4, s1
	s_add_u32 s0, s5, s0
	s_addc_u32 s1, s58, s1
	s_add_i32 s8, s38, s8
	s_mov_b32 s11, m0
	s_mov_b32 m0, s8
	s_nop 0
	global_load_lds_dwordx4 v212, s[6:7]
	s_mov_b32 m0, s11
	s_add_i32 s10, s8, 0x2000
	s_mov_b32 s6, m0
	s_mov_b32 m0, s10
	s_nop 0
	global_load_lds_dwordx4 v213, s[0:1]
	s_mov_b32 m0, s6
	s_addk_i32 s9, 0xff80
	s_add_i32 s0, s47, s50
	s_cmp_lt_i32 s0, s48
	s_cselect_b64 s[0:1], -1, 0
	s_cmp_gt_i32 s9, s49
	s_cselect_b64 s[6:7], -1, 0
	s_or_b64 s[0:1], s[0:1], s[6:7]
	s_and_b64 vcc, exec, s[0:1]
	s_cbranch_vccnz .LBB0_354
	s_and_b32 s34, s52, 0xc000
	v_add_u32_e32 v145, s47, v132
	s_movk_i32 s20, 0x100
	v_readfirstlane_b32 s30, v145
	s_nop 0
	s_sub_i32 s30, s30, 15
	s_cmp_le_u32 s30, 0xb2
	s_cbranch_scc1 .Lswa_loc_nomask
	v_add_u32_e32 v100, s34, v191
	v_add3_u32 v135, s34, v203, v198
	v_add_u32_e32 v102, v100, v193
	v_add_u32_e32 v100, v100, v192
	ds_read_b128 v[160:163], v100
	ds_read_b128 v[164:167], v102
	ds_read_b128 v[168:171], v100 offset:2048
	ds_read_b128 v[172:175], v102 offset:2048
	ds_read_b128 v[104:107], v100 offset:4096
	ds_read_b128 v[108:111], v102 offset:4096
	ds_read_b128 v[112:115], v100 offset:6144
	ds_read_b128 v[116:119], v102 offset:6144
	v_add_u32_e32 v103, v135, v199
	v_add_u32_e32 v133, v135, v200
	v_add_u32_e32 v134, v135, v201
	v_add_u32_e32 v135, v135, v202
	v_add_u32_e32 v244, 0, v145
	v_add_u32_e32 v245, 1, v145
	v_add_u32_e32 v246, 2, v145
	v_add_u32_e32 v247, 3, v145
	v_add_u32_e32 v248, 16, v145
	v_add_u32_e32 v249, 17, v145
	v_add_u32_e32 v250, 18, v145
	v_add_u32_e32 v251, 19, v145
	v_cmp_gt_u32_e64 s[0:1], v244, s20
	v_cmp_gt_u32_e64 s[6:7], v245, s20
	v_cmp_gt_u32_e64 s[8:9], v246, s20
	v_cmp_gt_u32_e64 s[10:11], v247, s20
	v_cmp_gt_u32_e64 s[12:13], v248, s20
	v_cmp_gt_u32_e64 s[24:25], v249, s20
	v_cmp_gt_u32_e64 s[26:27], v250, s20
	v_cmp_gt_u32_e64 s[28:29], v251, s20
	v_cndmask_b32_e64 v180, v0, v197, s[0:1]
	v_cndmask_b32_e64 v181, v0, v197, s[6:7]
	v_cndmask_b32_e64 v182, v0, v197, s[8:9]
	v_cndmask_b32_e64 v183, v0, v197, s[10:11]
	v_cndmask_b32_e64 v236, v0, v197, s[12:13]
	v_cndmask_b32_e64 v237, v0, v197, s[24:25]
	v_cndmask_b32_e64 v238, v0, v197, s[26:27]
	v_cndmask_b32_e64 v239, v0, v197, s[28:29]
	v_add_u32_e32 v244, 32, v145
	v_add_u32_e32 v245, 33, v145
	v_add_u32_e32 v246, 34, v145
	v_add_u32_e32 v247, 35, v145
	v_add_u32_e32 v248, 48, v145
	v_add_u32_e32 v249, 49, v145
	v_add_u32_e32 v250, 50, v145
	v_add_u32_e32 v251, 51, v145
	v_cmp_gt_u32_e64 s[0:1], v244, s20
	v_cmp_gt_u32_e64 s[6:7], v245, s20
	v_cmp_gt_u32_e64 s[8:9], v246, s20
	v_cmp_gt_u32_e64 s[10:11], v247, s20
	v_cmp_gt_u32_e64 s[12:13], v248, s20
	v_cmp_gt_u32_e64 s[24:25], v249, s20
	v_cmp_gt_u32_e64 s[26:27], v250, s20
	v_cmp_gt_u32_e64 s[28:29], v251, s20
	v_cndmask_b32_e64 v252, v0, v197, s[0:1]
	v_cndmask_b32_e64 v253, v0, v197, s[6:7]
	v_cndmask_b32_e64 v254, v0, v197, s[8:9]
	v_cndmask_b32_e64 v255, v0, v197, s[10:11]
	v_cndmask_b32_e64 v204, v0, v197, s[12:13]
	v_cndmask_b32_e64 v205, v0, v197, s[24:25]
	v_cndmask_b32_e64 v206, v0, v197, s[26:27]
	v_cndmask_b32_e64 v207, v0, v197, s[28:29]
	s_waitcnt lgkmcnt(4)
	v_mfma_f32_16x16x32_bf16 v[136:139], v[160:163], v[4:7], v[180:183]
	v_mfma_f32_16x16x32_bf16 v[140:143], v[168:171], v[4:7], v[236:239]
	v_mfma_f32_16x16x32_bf16 v[136:139], v[164:167], v[12:15], v[136:139]
	v_mfma_f32_16x16x32_bf16 v[140:143], v[172:175], v[12:15], v[140:143]
	ds_read_b64_tr_b16 v[216:217], v103 offset:8192
	ds_read_b64_tr_b16 v[218:219], v103 offset:10240
	ds_read_b64_tr_b16 v[220:221], v133 offset:8192
	ds_read_b64_tr_b16 v[222:223], v133 offset:10240
	ds_read_b64_tr_b16 v[224:225], v134 offset:8192
	ds_read_b64_tr_b16 v[226:227], v134 offset:10240
	ds_read_b64_tr_b16 v[228:229], v135 offset:8192
	ds_read_b64_tr_b16 v[230:231], v135 offset:10240
	v_mfma_f32_16x16x32_bf16 v[176:179], v[160:163], v[8:11], v[180:183]
	v_exp_f32_e32 v136, v136
	v_exp_f32_e32 v137, v137
	v_exp_f32_e32 v138, v138
	v_add_f32_e32 v144, v136, v137
	v_mfma_f32_16x16x32_bf16 v[232:235], v[168:171], v[8:11], v[236:239]
	v_exp_f32_e32 v139, v139
	v_add_f32_e32 v144, v144, v138
	v_exp_f32_e32 v140, v140
	v_add_f32_e32 v144, v144, v139
	v_mfma_f32_16x16x32_bf16 v[176:179], v[164:167], v[16:19], v[176:179]
	v_exp_f32_e32 v141, v141
	v_add_f32_e32 v144, v144, v140
	v_exp_f32_e32 v142, v142
	v_add_f32_e32 v144, v144, v141
	v_cvt_pk_bf16_f32 v136, v136, v137
	v_mfma_f32_16x16x32_bf16 v[232:235], v[172:175], v[16:19], v[232:235]
	v_exp_f32_e32 v143, v143
	v_add_f32_e32 v144, v144, v142
	v_cvt_pk_bf16_f32 v137, v138, v139
	v_cvt_pk_bf16_f32 v138, v140, v141
	v_cvt_pk_bf16_f32 v139, v142, v143
	v_add_f32_e32 v144, v144, v143
	v_add_f32_e32 v131, v131, v144
	s_waitcnt lgkmcnt(0)
; #define LAS __attribute__((address_space(3)))
; __device__ __forceinline__ s16x4 vtr(const LAS unsigned char* p) { return __builtin_bit_cast(s16x4, __builtin_amdgcn_ds_read_tr16_b64_v4i16((LAS v4i16_t*)p)); }
;     const int l15 = lane & 15, g = lane >> 4, q4 = l15 >> 2;
;     const LAS unsigned char* kb0 = Kt + l15 * 128;
;     const int kx0 = ((g) ^ (l15 & 7)) << 4, kx1 = ((4 + g) ^ (l15 & 7)) << 4;
;     const LAS unsigned char* vrow = Vt + (4 * g + q4) * 128 + (lane & 3) * 8;
;     const int swz = (2 * (g & 1) + (q4 >> 1)) & 3;
;     const f32x4 cinit = (f32x4){negb, negb, negb, negb};
; #pragma unroll
;     for (int gh = 0; gh < 4 / GPB; ++gh) {
;         f32x4 S[GPB][4];
; #pragma unroll
;         for (int kb = 0; kb < 4; ++kb) {
;             const bf16x8 kf0 = *(const LAS bf16x8*)(kb0 + (16 * kb) * 128 + kx0), kf1 = *(const LAS bf16x8*)(kb0 + (16 * kb) * 128 + kx1);
; #pragma unroll
;             for (int gi = 0; gi < GPB; ++gi) { S[gi][kb] = __builtin_amdgcn_mfma_f32_16x16x32_bf16(kf0, qf[GPB * gh + gi][0], cinit, 0, 0, 0);
;                 S[gi][kb] = __builtin_amdgcn_mfma_f32_16x16x32_bf16(kf1, qf[GPB * gh + gi][1], S[gi][kb], 0, 0, 0); } }
;         bf16x8 pf[GPB][2];
; #pragma unroll
;         for (int gi = 0; gi < GPB; ++gi) {
;             if (MASK) {
; #pragma unroll
;                 for (int kb = 0; kb < 4; ++kb)
; #pragma unroll
;                     for (int i = 0; i < 4; ++i) { const int rel = rel0 + 16 * kb + 4 * g + i; S[gi][kb][i] = ((unsigned)(rel + 128) > 256u) ? NEGBIG : S[gi][kb][i]; }
;             }
;             ls[GPB * gh + gi] += exp_step<4>(S[gi]);
;             pf[gi][0] = pack8(S[gi][0], S[gi][1]); pf[gi][1] = pack8(S[gi][2], S[gi][3]);
;         }
; #pragma unroll
;         for (int kc = 0; kc < 2; ++kc)
; #pragma unroll
;             for (int db = 0; db < 4; ++db) {
;                 const LAS unsigned char* va = vrow + ((db ^ swz) << 5) + (32 * kc) * 128;
;                 const bf16x8 vf = cat8(vtr(va), vtr(va + 16 * 128));
; #pragma unroll
;                 for (int gi = 0; gi < GPB; ++gi) O[GPB * gh + gi][db] = __builtin_amdgcn_mfma_f32_16x16x32_bf16(vf, pf[gi][kc], O[GPB * gh + gi][db], 0, 0, 0);
;             }
;         if (SB == 1) __builtin_amdgcn_sched_barrier(0); else if (SB == 2) __builtin_amdgcn_sched_barrier(0x108);
;     }
; }
	v_mfma_f32_16x16x32_bf16 v[244:247], v[160:163], v[20:23], v[180:183]
	v_exp_f32_e32 v176, v176
	v_exp_f32_e32 v177, v177
	v_mfma_f32_16x16x32_bf16 v[248:251], v[168:171], v[20:23], v[236:239]
	v_exp_f32_e32 v178, v178
	v_add_f32_e32 v144, v176, v177
	v_mfma_f32_16x16x32_bf16 v[244:247], v[164:167], v[24:27], v[244:247]
	v_exp_f32_e32 v179, v179
	v_add_f32_e32 v144, v144, v178
	v_mfma_f32_16x16x32_bf16 v[248:251], v[172:175], v[24:27], v[248:251]
	v_exp_f32_e32 v232, v232
	v_add_f32_e32 v144, v144, v179
	v_mfma_f32_16x16x32_bf16 v[64:67], v[216:219], v[136:139], v[64:67]
	v_exp_f32_e32 v233, v233
	v_add_f32_e32 v144, v144, v232
	v_mfma_f32_16x16x32_bf16 v[60:63], v[220:223], v[136:139], v[60:63]
	v_exp_f32_e32 v234, v234
	v_add_f32_e32 v144, v144, v233
	v_cvt_pk_bf16_f32 v176, v176, v177
	v_mfma_f32_16x16x32_bf16 v[56:59], v[224:227], v[136:139], v[56:59]
	v_exp_f32_e32 v235, v235
	v_add_f32_e32 v144, v144, v234
	v_cvt_pk_bf16_f32 v177, v178, v179
	v_mfma_f32_16x16x32_bf16 v[52:55], v[228:231], v[136:139], v[52:55]
	v_cvt_pk_bf16_f32 v178, v232, v233
	v_cvt_pk_bf16_f32 v179, v234, v235
	v_add_f32_e32 v144, v144, v235
	v_add_f32_e32 v130, v130, v144
	v_mfma_f32_16x16x32_bf16 v[136:139], v[160:163], v[28:31], v[180:183]
	v_exp_f32_e32 v244, v244
	v_exp_f32_e32 v245, v245
	v_mfma_f32_16x16x32_bf16 v[140:143], v[168:171], v[28:31], v[236:239]
	v_exp_f32_e32 v246, v246
	v_add_f32_e32 v144, v244, v245
	v_mfma_f32_16x16x32_bf16 v[136:139], v[164:167], v[32:35], v[136:139]
	v_exp_f32_e32 v247, v247
	v_add_f32_e32 v144, v144, v246
	v_mfma_f32_16x16x32_bf16 v[140:143], v[172:175], v[32:35], v[140:143]
	v_exp_f32_e32 v248, v248
	v_add_f32_e32 v144, v144, v247
	v_mfma_f32_16x16x32_bf16 v[48:51], v[216:219], v[176:179], v[48:51]
	v_exp_f32_e32 v249, v249
	v_add_f32_e32 v144, v144, v248
	v_mfma_f32_16x16x32_bf16 v[44:47], v[220:223], v[176:179], v[44:47]
	v_exp_f32_e32 v250, v250
	v_add_f32_e32 v144, v144, v249
	v_cvt_pk_bf16_f32 v244, v244, v245
	v_mfma_f32_16x16x32_bf16 v[40:43], v[224:227], v[176:179], v[40:43]
	v_exp_f32_e32 v251, v251
	v_add_f32_e32 v144, v144, v250
	v_cvt_pk_bf16_f32 v245, v246, v247
	v_mfma_f32_16x16x32_bf16 v[36:39], v[228:231], v[176:179], v[36:39]
	v_cvt_pk_bf16_f32 v246, v248, v249
	v_cvt_pk_bf16_f32 v247, v250, v251
	v_add_f32_e32 v144, v144, v251
	v_add_f32_e32 v129, v129, v144
	ds_read_b64_tr_b16 v[160:161], v103 offset:12288
	ds_read_b64_tr_b16 v[162:163], v103 offset:14336
	ds_read_b64_tr_b16 v[164:165], v133 offset:12288
	ds_read_b64_tr_b16 v[166:167], v133 offset:14336
	ds_read_b64_tr_b16 v[168:169], v134 offset:12288
	ds_read_b64_tr_b16 v[170:171], v134 offset:14336
	ds_read_b64_tr_b16 v[172:173], v135 offset:12288
	ds_read_b64_tr_b16 v[174:175], v135 offset:14336
	v_mfma_f32_16x16x32_bf16 v[176:179], v[104:107], v[4:7], v[252:255]
	v_exp_f32_e32 v136, v136
	v_exp_f32_e32 v137, v137
	v_mfma_f32_16x16x32_bf16 v[232:235], v[112:115], v[4:7], v[204:207]
	v_exp_f32_e32 v138, v138
	v_add_f32_e32 v144, v136, v137
	v_mfma_f32_16x16x32_bf16 v[176:179], v[108:111], v[12:15], v[176:179]
	v_exp_f32_e32 v139, v139
	v_add_f32_e32 v144, v144, v138
	v_mfma_f32_16x16x32_bf16 v[232:235], v[116:119], v[12:15], v[232:235]
	v_exp_f32_e32 v140, v140
	v_add_f32_e32 v144, v144, v139
	v_mfma_f32_16x16x32_bf16 v[72:75], v[216:219], v[244:247], v[72:75]
	v_exp_f32_e32 v141, v141
	v_add_f32_e32 v144, v144, v140
	v_mfma_f32_16x16x32_bf16 v[84:87], v[220:223], v[244:247], v[84:87]
	v_exp_f32_e32 v142, v142
	v_add_f32_e32 v144, v144, v141
	v_cvt_pk_bf16_f32 v136, v136, v137
	v_mfma_f32_16x16x32_bf16 v[88:91], v[224:227], v[244:247], v[88:91]
	v_exp_f32_e32 v143, v143
	v_add_f32_e32 v144, v144, v142
	v_cvt_pk_bf16_f32 v137, v138, v139
	v_mfma_f32_16x16x32_bf16 v[96:99], v[228:231], v[244:247], v[96:99]
	v_cvt_pk_bf16_f32 v138, v140, v141
	v_cvt_pk_bf16_f32 v139, v142, v143
	v_add_f32_e32 v144, v144, v143
	v_add_f32_e32 v128, v128, v144
	v_mfma_f32_16x16x32_bf16 v[244:247], v[104:107], v[8:11], v[252:255]
	v_exp_f32_e32 v176, v176
	v_exp_f32_e32 v177, v177
	v_mfma_f32_16x16x32_bf16 v[248:251], v[112:115], v[8:11], v[204:207]
	v_exp_f32_e32 v178, v178
	v_add_f32_e32 v144, v176, v177
	v_mfma_f32_16x16x32_bf16 v[244:247], v[108:111], v[16:19], v[244:247]
	v_exp_f32_e32 v179, v179
	v_add_f32_e32 v144, v144, v178
	v_mfma_f32_16x16x32_bf16 v[248:251], v[116:119], v[16:19], v[248:251]
	v_exp_f32_e32 v232, v232
	v_add_f32_e32 v144, v144, v179
	v_mfma_f32_16x16x32_bf16 v[68:71], v[216:219], v[136:139], v[68:71]
	v_exp_f32_e32 v233, v233
	v_add_f32_e32 v144, v144, v232
	v_mfma_f32_16x16x32_bf16 v[76:79], v[220:223], v[136:139], v[76:79]
	v_exp_f32_e32 v234, v234
	v_add_f32_e32 v144, v144, v233
	v_cvt_pk_bf16_f32 v176, v176, v177
	v_mfma_f32_16x16x32_bf16 v[80:83], v[224:227], v[136:139], v[80:83]
	v_exp_f32_e32 v235, v235
	v_add_f32_e32 v144, v144, v234
	v_cvt_pk_bf16_f32 v177, v178, v179
	v_mfma_f32_16x16x32_bf16 v[92:95], v[228:231], v[136:139], v[92:95]
	v_cvt_pk_bf16_f32 v178, v232, v233
	v_cvt_pk_bf16_f32 v179, v234, v235
	v_add_f32_e32 v144, v144, v235
	v_add_f32_e32 v131, v131, v144
	s_waitcnt lgkmcnt(0)
; #define LAS __attribute__((address_space(3)))
; __device__ __forceinline__ s16x4 vtr(const LAS unsigned char* p) { return __builtin_bit_cast(s16x4, __builtin_amdgcn_ds_read_tr16_b64_v4i16((LAS v4i16_t*)p)); }
;     const int l15 = lane & 15, g = lane >> 4, q4 = l15 >> 2;
;     const LAS unsigned char* kb0 = Kt + l15 * 128;
;     const int kx0 = ((g) ^ (l15 & 7)) << 4, kx1 = ((4 + g) ^ (l15 & 7)) << 4;
;     const LAS unsigned char* vrow = Vt + (4 * g + q4) * 128 + (lane & 3) * 8;
;     const int swz = (2 * (g & 1) + (q4 >> 1)) & 3;
;     const f32x4 cinit = (f32x4){negb, negb, negb, negb};
; #pragma unroll
;     for (int gh = 0; gh < 4 / GPB; ++gh) {
;         f32x4 S[GPB][4];
; #pragma unroll
;         for (int kb = 0; kb < 4; ++kb) {
;             const bf16x8 kf0 = *(const LAS bf16x8*)(kb0 + (16 * kb) * 128 + kx0), kf1 = *(const LAS bf16x8*)(kb0 + (16 * kb) * 128 + kx1);
; #pragma unroll
;             for (int gi = 0; gi < GPB; ++gi) { S[gi][kb] = __builtin_amdgcn_mfma_f32_16x16x32_bf16(kf0, qf[GPB * gh + gi][0], cinit, 0, 0, 0);
;                 S[gi][kb] = __builtin_amdgcn_mfma_f32_16x16x32_bf16(kf1, qf[GPB * gh + gi][1], S[gi][kb], 0, 0, 0); } }
;         bf16x8 pf[GPB][2];
; #pragma unroll
;         for (int gi = 0; gi < GPB; ++gi) {
;             if (MASK) {
; #pragma unroll
;                 for (int kb = 0; kb < 4; ++kb)
; #pragma unroll
;                     for (int i = 0; i < 4; ++i) { const int rel = rel0 + 16 * kb + 4 * g + i; S[gi][kb][i] = ((unsigned)(rel + 128) > 256u) ? NEGBIG : S[gi][kb][i]; }
;             }
;             ls[GPB * gh + gi] += exp_step<4>(S[gi]);
;             pf[gi][0] = pack8(S[gi][0], S[gi][1]); pf[gi][1] = pack8(S[gi][2], S[gi][3]);
;         }
; #pragma unroll
;         for (int kc = 0; kc < 2; ++kc)
; #pragma unroll
;             for (int db = 0; db < 4; ++db) {
;                 const LAS unsigned char* va = vrow + ((db ^ swz) << 5) + (32 * kc) * 128;
;                 const bf16x8 vf = cat8(vtr(va), vtr(va + 16 * 128));
; #pragma unroll
;                 for (int gi = 0; gi < GPB; ++gi) O[GPB * gh + gi][db] = __builtin_amdgcn_mfma_f32_16x16x32_bf16(vf, pf[gi][kc], O[GPB * gh + gi][db], 0, 0, 0);
;             }
;         if (SB == 1) __builtin_amdgcn_sched_barrier(0); else if (SB == 2) __builtin_amdgcn_sched_barrier(0x108);
;     }
; }
	v_mfma_f32_16x16x32_bf16 v[136:139], v[104:107], v[20:23], v[252:255]
	v_exp_f32_e32 v244, v244
	v_exp_f32_e32 v245, v245
	v_mfma_f32_16x16x32_bf16 v[140:143], v[112:115], v[20:23], v[204:207]
	v_exp_f32_e32 v246, v246
	v_add_f32_e32 v144, v244, v245
	v_mfma_f32_16x16x32_bf16 v[136:139], v[108:111], v[24:27], v[136:139]
	v_exp_f32_e32 v247, v247
	v_add_f32_e32 v144, v144, v246
	v_mfma_f32_16x16x32_bf16 v[140:143], v[116:119], v[24:27], v[140:143]
	v_exp_f32_e32 v248, v248
	v_add_f32_e32 v144, v144, v247
	v_mfma_f32_16x16x32_bf16 v[64:67], v[160:163], v[176:179], v[64:67]
	v_exp_f32_e32 v249, v249
	v_add_f32_e32 v144, v144, v248
	v_mfma_f32_16x16x32_bf16 v[60:63], v[164:167], v[176:179], v[60:63]
	v_exp_f32_e32 v250, v250
	v_add_f32_e32 v144, v144, v249
	v_cvt_pk_bf16_f32 v244, v244, v245
	v_mfma_f32_16x16x32_bf16 v[56:59], v[168:171], v[176:179], v[56:59]
	v_exp_f32_e32 v251, v251
	v_add_f32_e32 v144, v144, v250
	v_cvt_pk_bf16_f32 v245, v246, v247
	v_mfma_f32_16x16x32_bf16 v[52:55], v[172:175], v[176:179], v[52:55]
	v_cvt_pk_bf16_f32 v246, v248, v249
	v_cvt_pk_bf16_f32 v247, v250, v251
	v_add_f32_e32 v144, v144, v251
	v_add_f32_e32 v130, v130, v144
	v_mfma_f32_16x16x32_bf16 v[176:179], v[104:107], v[28:31], v[252:255]
	v_exp_f32_e32 v136, v136
	v_exp_f32_e32 v137, v137
	v_mfma_f32_16x16x32_bf16 v[232:235], v[112:115], v[28:31], v[204:207]
	v_exp_f32_e32 v138, v138
	v_add_f32_e32 v144, v136, v137
	v_mfma_f32_16x16x32_bf16 v[176:179], v[108:111], v[32:35], v[176:179]
	v_exp_f32_e32 v139, v139
	v_add_f32_e32 v144, v144, v138
	v_mfma_f32_16x16x32_bf16 v[232:235], v[116:119], v[32:35], v[232:235]
	v_exp_f32_e32 v140, v140
	v_add_f32_e32 v144, v144, v139
	v_mfma_f32_16x16x32_bf16 v[48:51], v[160:163], v[244:247], v[48:51]
	v_exp_f32_e32 v141, v141
	v_add_f32_e32 v144, v144, v140
	v_mfma_f32_16x16x32_bf16 v[44:47], v[164:167], v[244:247], v[44:47]
	v_exp_f32_e32 v142, v142
	v_add_f32_e32 v144, v144, v141
	v_cvt_pk_bf16_f32 v136, v136, v137
	v_mfma_f32_16x16x32_bf16 v[40:43], v[168:171], v[244:247], v[40:43]
	v_exp_f32_e32 v143, v143
	v_add_f32_e32 v144, v144, v142
	v_cvt_pk_bf16_f32 v137, v138, v139
	v_mfma_f32_16x16x32_bf16 v[36:39], v[172:175], v[244:247], v[36:39]
	v_cvt_pk_bf16_f32 v138, v140, v141
	v_cvt_pk_bf16_f32 v139, v142, v143
	v_add_f32_e32 v144, v144, v143
	v_add_f32_e32 v129, v129, v144
	v_mfma_f32_16x16x32_bf16 v[72:75], v[160:163], v[136:139], v[72:75]
	v_exp_f32_e32 v176, v176
	v_exp_f32_e32 v177, v177
	v_exp_f32_e32 v178, v178
	v_add_f32_e32 v144, v176, v177
	v_mfma_f32_16x16x32_bf16 v[84:87], v[164:167], v[136:139], v[84:87]
	v_exp_f32_e32 v179, v179
	v_add_f32_e32 v144, v144, v178
	v_exp_f32_e32 v232, v232
	v_add_f32_e32 v144, v144, v179
	v_mfma_f32_16x16x32_bf16 v[88:91], v[168:171], v[136:139], v[88:91]
	v_exp_f32_e32 v233, v233
	v_add_f32_e32 v144, v144, v232
	v_exp_f32_e32 v234, v234
	v_add_f32_e32 v144, v144, v233
	v_cvt_pk_bf16_f32 v176, v176, v177
	v_mfma_f32_16x16x32_bf16 v[96:99], v[172:175], v[136:139], v[96:99]
	v_exp_f32_e32 v235, v235
	v_add_f32_e32 v144, v144, v234
	v_cvt_pk_bf16_f32 v177, v178, v179
	v_cvt_pk_bf16_f32 v178, v232, v233
	v_cvt_pk_bf16_f32 v179, v234, v235
	v_add_f32_e32 v144, v144, v235
	v_add_f32_e32 v128, v128, v144
	v_mfma_f32_16x16x32_bf16 v[68:71], v[160:163], v[176:179], v[68:71]
	v_mfma_f32_16x16x32_bf16 v[76:79], v[164:167], v[176:179], v[76:79]
	v_mfma_f32_16x16x32_bf16 v[80:83], v[168:171], v[176:179], v[80:83]
	v_mfma_f32_16x16x32_bf16 v[92:95], v[172:175], v[176:179], v[92:95]
	s_branch .LBB0_354
.Lswa_loc_nomask:
	v_add_u32_e32 v100, s34, v191
	v_add3_u32 v135, s34, v203, v198
	v_add_u32_e32 v102, v100, v193
	v_add_u32_e32 v100, v100, v192
	ds_read_b128 v[160:163], v100
	ds_read_b128 v[164:167], v102
	ds_read_b128 v[168:171], v100 offset:2048
	ds_read_b128 v[172:175], v102 offset:2048
	ds_read_b128 v[104:107], v100 offset:4096
	ds_read_b128 v[108:111], v102 offset:4096
	ds_read_b128 v[112:115], v100 offset:6144
	ds_read_b128 v[116:119], v102 offset:6144
	v_add_u32_e32 v103, v135, v199
	v_add_u32_e32 v133, v135, v200
	v_add_u32_e32 v134, v135, v201
	v_add_u32_e32 v135, v135, v202
	s_waitcnt lgkmcnt(4)
	v_mfma_f32_16x16x32_bf16 v[136:139], v[160:163], v[4:7], v[0:3]
	v_mfma_f32_16x16x32_bf16 v[140:143], v[168:171], v[4:7], v[0:3]
	v_mfma_f32_16x16x32_bf16 v[136:139], v[164:167], v[12:15], v[136:139]
	v_mfma_f32_16x16x32_bf16 v[140:143], v[172:175], v[12:15], v[140:143]
	ds_read_b64_tr_b16 v[216:217], v103 offset:8192
	ds_read_b64_tr_b16 v[218:219], v103 offset:10240
	ds_read_b64_tr_b16 v[220:221], v133 offset:8192
	ds_read_b64_tr_b16 v[222:223], v133 offset:10240
	ds_read_b64_tr_b16 v[224:225], v134 offset:8192
	ds_read_b64_tr_b16 v[226:227], v134 offset:10240
	ds_read_b64_tr_b16 v[228:229], v135 offset:8192
	ds_read_b64_tr_b16 v[230:231], v135 offset:10240
	v_mfma_f32_16x16x32_bf16 v[176:179], v[160:163], v[8:11], v[0:3]
	v_exp_f32_e32 v136, v136
	v_exp_f32_e32 v137, v137
	v_exp_f32_e32 v138, v138
	v_add_f32_e32 v144, v136, v137
	v_mfma_f32_16x16x32_bf16 v[232:235], v[168:171], v[8:11], v[0:3]
	v_exp_f32_e32 v139, v139
	v_add_f32_e32 v144, v144, v138
	v_exp_f32_e32 v140, v140
	v_add_f32_e32 v144, v144, v139
	v_mfma_f32_16x16x32_bf16 v[176:179], v[164:167], v[16:19], v[176:179]
	v_exp_f32_e32 v141, v141
	v_add_f32_e32 v144, v144, v140
	v_exp_f32_e32 v142, v142
	v_add_f32_e32 v144, v144, v141
	v_cvt_pk_bf16_f32 v136, v136, v137
	v_mfma_f32_16x16x32_bf16 v[232:235], v[172:175], v[16:19], v[232:235]
	v_exp_f32_e32 v143, v143
	v_add_f32_e32 v144, v144, v142
	v_cvt_pk_bf16_f32 v137, v138, v139
	v_cvt_pk_bf16_f32 v138, v140, v141
	v_cvt_pk_bf16_f32 v139, v142, v143
	v_add_f32_e32 v144, v144, v143
	v_add_f32_e32 v131, v131, v144
	s_waitcnt lgkmcnt(0)
; #define LAS __attribute__((address_space(3)))
; __device__ __forceinline__ s16x4 vtr(const LAS unsigned char* p) { return __builtin_bit_cast(s16x4, __builtin_amdgcn_ds_read_tr16_b64_v4i16((LAS v4i16_t*)p)); }
;     const int l15 = lane & 15, g = lane >> 4, q4 = l15 >> 2;
;     const LAS unsigned char* kb0 = Kt + l15 * 128;
;     const int kx0 = ((g) ^ (l15 & 7)) << 4, kx1 = ((4 + g) ^ (l15 & 7)) << 4;
;     const LAS unsigned char* vrow = Vt + (4 * g + q4) * 128 + (lane & 3) * 8;
;     const int swz = (2 * (g & 1) + (q4 >> 1)) & 3;
;     const f32x4 cinit = (f32x4){negb, negb, negb, negb};
; #pragma unroll
;     for (int gh = 0; gh < 4 / GPB; ++gh) {
;         f32x4 S[GPB][4];
; #pragma unroll
;         for (int kb = 0; kb < 4; ++kb) {
;             const bf16x8 kf0 = *(const LAS bf16x8*)(kb0 + (16 * kb) * 128 + kx0), kf1 = *(const LAS bf16x8*)(kb0 + (16 * kb) * 128 + kx1);
; #pragma unroll
;             for (int gi = 0; gi < GPB; ++gi) { S[gi][kb] = __builtin_amdgcn_mfma_f32_16x16x32_bf16(kf0, qf[GPB * gh + gi][0], cinit, 0, 0, 0);
;                 S[gi][kb] = __builtin_amdgcn_mfma_f32_16x16x32_bf16(kf1, qf[GPB * gh + gi][1], S[gi][kb], 0, 0, 0); } }
;         bf16x8 pf[GPB][2];
; #pragma unroll
;         for (int gi = 0; gi < GPB; ++gi) {
;             if (MASK) {
; #pragma unroll
;                 for (int kb = 0; kb < 4; ++kb)
; #pragma unroll
;                     for (int i = 0; i < 4; ++i) { const int rel = rel0 + 16 * kb + 4 * g + i; S[gi][kb][i] = ((unsigned)(rel + 128) > 256u) ? NEGBIG : S[gi][kb][i]; }
;             }
;             ls[GPB * gh + gi] += exp_step<4>(S[gi]);
;             pf[gi][0] = pack8(S[gi][0], S[gi][1]); pf[gi][1] = pack8(S[gi][2], S[gi][3]);
;         }
; #pragma unroll
;         for (int kc = 0; kc < 2; ++kc)
; #pragma unroll
;             for (int db = 0; db < 4; ++db) {
;                 const LAS unsigned char* va = vrow + ((db ^ swz) << 5) + (32 * kc) * 128;
;                 const bf16x8 vf = cat8(vtr(va), vtr(va + 16 * 128));
; #pragma unroll
;                 for (int gi = 0; gi < GPB; ++gi) O[GPB * gh + gi][db] = __builtin_amdgcn_mfma_f32_16x16x32_bf16(vf, pf[gi][kc], O[GPB * gh + gi][db], 0, 0, 0);
;             }
;         if (SB == 1) __builtin_amdgcn_sched_barrier(0); else if (SB == 2) __builtin_amdgcn_sched_barrier(0x108);
;     }
; }
	v_mfma_f32_16x16x32_bf16 v[244:247], v[160:163], v[20:23], v[0:3]
	v_exp_f32_e32 v176, v176
	v_exp_f32_e32 v177, v177
	v_mfma_f32_16x16x32_bf16 v[248:251], v[168:171], v[20:23], v[0:3]
	v_exp_f32_e32 v178, v178
	v_add_f32_e32 v144, v176, v177
	v_mfma_f32_16x16x32_bf16 v[244:247], v[164:167], v[24:27], v[244:247]
	v_exp_f32_e32 v179, v179
	v_add_f32_e32 v144, v144, v178
	v_mfma_f32_16x16x32_bf16 v[248:251], v[172:175], v[24:27], v[248:251]
	v_exp_f32_e32 v232, v232
	v_add_f32_e32 v144, v144, v179
	v_mfma_f32_16x16x32_bf16 v[64:67], v[216:219], v[136:139], v[64:67]
	v_exp_f32_e32 v233, v233
	v_add_f32_e32 v144, v144, v232
	v_mfma_f32_16x16x32_bf16 v[60:63], v[220:223], v[136:139], v[60:63]
	v_exp_f32_e32 v234, v234
	v_add_f32_e32 v144, v144, v233
	v_cvt_pk_bf16_f32 v176, v176, v177
	v_mfma_f32_16x16x32_bf16 v[56:59], v[224:227], v[136:139], v[56:59]
	v_exp_f32_e32 v235, v235
	v_add_f32_e32 v144, v144, v234
	v_cvt_pk_bf16_f32 v177, v178, v179
	v_mfma_f32_16x16x32_bf16 v[52:55], v[228:231], v[136:139], v[52:55]
	v_cvt_pk_bf16_f32 v178, v232, v233
	v_cvt_pk_bf16_f32 v179, v234, v235
	v_add_f32_e32 v144, v144, v235
	v_add_f32_e32 v130, v130, v144
	v_mfma_f32_16x16x32_bf16 v[136:139], v[160:163], v[28:31], v[0:3]
	v_exp_f32_e32 v244, v244
	v_exp_f32_e32 v245, v245
	v_mfma_f32_16x16x32_bf16 v[140:143], v[168:171], v[28:31], v[0:3]
	v_exp_f32_e32 v246, v246
	v_add_f32_e32 v144, v244, v245
	v_mfma_f32_16x16x32_bf16 v[136:139], v[164:167], v[32:35], v[136:139]
	v_exp_f32_e32 v247, v247
	v_add_f32_e32 v144, v144, v246
	v_mfma_f32_16x16x32_bf16 v[140:143], v[172:175], v[32:35], v[140:143]
	v_exp_f32_e32 v248, v248
	v_add_f32_e32 v144, v144, v247
	v_mfma_f32_16x16x32_bf16 v[48:51], v[216:219], v[176:179], v[48:51]
	v_exp_f32_e32 v249, v249
	v_add_f32_e32 v144, v144, v248
	v_mfma_f32_16x16x32_bf16 v[44:47], v[220:223], v[176:179], v[44:47]
	v_exp_f32_e32 v250, v250
	v_add_f32_e32 v144, v144, v249
	v_cvt_pk_bf16_f32 v244, v244, v245
	v_mfma_f32_16x16x32_bf16 v[40:43], v[224:227], v[176:179], v[40:43]
	v_exp_f32_e32 v251, v251
	v_add_f32_e32 v144, v144, v250
	v_cvt_pk_bf16_f32 v245, v246, v247
	v_mfma_f32_16x16x32_bf16 v[36:39], v[228:231], v[176:179], v[36:39]
	v_cvt_pk_bf16_f32 v246, v248, v249
	v_cvt_pk_bf16_f32 v247, v250, v251
	v_add_f32_e32 v144, v144, v251
	v_add_f32_e32 v129, v129, v144
	ds_read_b64_tr_b16 v[160:161], v103 offset:12288
	ds_read_b64_tr_b16 v[162:163], v103 offset:14336
	ds_read_b64_tr_b16 v[164:165], v133 offset:12288
	ds_read_b64_tr_b16 v[166:167], v133 offset:14336
	ds_read_b64_tr_b16 v[168:169], v134 offset:12288
	ds_read_b64_tr_b16 v[170:171], v134 offset:14336
	ds_read_b64_tr_b16 v[172:173], v135 offset:12288
	ds_read_b64_tr_b16 v[174:175], v135 offset:14336
	v_mfma_f32_16x16x32_bf16 v[176:179], v[104:107], v[4:7], v[0:3]
	v_exp_f32_e32 v136, v136
	v_exp_f32_e32 v137, v137
	v_mfma_f32_16x16x32_bf16 v[232:235], v[112:115], v[4:7], v[0:3]
	v_exp_f32_e32 v138, v138
	v_add_f32_e32 v144, v136, v137
	v_mfma_f32_16x16x32_bf16 v[176:179], v[108:111], v[12:15], v[176:179]
	v_exp_f32_e32 v139, v139
	v_add_f32_e32 v144, v144, v138
	v_mfma_f32_16x16x32_bf16 v[232:235], v[116:119], v[12:15], v[232:235]
	v_exp_f32_e32 v140, v140
	v_add_f32_e32 v144, v144, v139
	v_mfma_f32_16x16x32_bf16 v[72:75], v[216:219], v[244:247], v[72:75]
	v_exp_f32_e32 v141, v141
	v_add_f32_e32 v144, v144, v140
	v_mfma_f32_16x16x32_bf16 v[84:87], v[220:223], v[244:247], v[84:87]
	v_exp_f32_e32 v142, v142
	v_add_f32_e32 v144, v144, v141
	v_cvt_pk_bf16_f32 v136, v136, v137
	v_mfma_f32_16x16x32_bf16 v[88:91], v[224:227], v[244:247], v[88:91]
	v_exp_f32_e32 v143, v143
	v_add_f32_e32 v144, v144, v142
	v_cvt_pk_bf16_f32 v137, v138, v139
	v_mfma_f32_16x16x32_bf16 v[96:99], v[228:231], v[244:247], v[96:99]
	v_cvt_pk_bf16_f32 v138, v140, v141
	v_cvt_pk_bf16_f32 v139, v142, v143
	v_add_f32_e32 v144, v144, v143
	v_add_f32_e32 v128, v128, v144
	v_mfma_f32_16x16x32_bf16 v[244:247], v[104:107], v[8:11], v[0:3]
	v_exp_f32_e32 v176, v176
	v_exp_f32_e32 v177, v177
	v_mfma_f32_16x16x32_bf16 v[248:251], v[112:115], v[8:11], v[0:3]
	v_exp_f32_e32 v178, v178
	v_add_f32_e32 v144, v176, v177
	v_mfma_f32_16x16x32_bf16 v[244:247], v[108:111], v[16:19], v[244:247]
	v_exp_f32_e32 v179, v179
	v_add_f32_e32 v144, v144, v178
	v_mfma_f32_16x16x32_bf16 v[248:251], v[116:119], v[16:19], v[248:251]
	v_exp_f32_e32 v232, v232
	v_add_f32_e32 v144, v144, v179
	v_mfma_f32_16x16x32_bf16 v[68:71], v[216:219], v[136:139], v[68:71]
	v_exp_f32_e32 v233, v233
	v_add_f32_e32 v144, v144, v232
	v_mfma_f32_16x16x32_bf16 v[76:79], v[220:223], v[136:139], v[76:79]
	v_exp_f32_e32 v234, v234
	v_add_f32_e32 v144, v144, v233
	v_cvt_pk_bf16_f32 v176, v176, v177
	v_mfma_f32_16x16x32_bf16 v[80:83], v[224:227], v[136:139], v[80:83]
	v_exp_f32_e32 v235, v235
	v_add_f32_e32 v144, v144, v234
	v_cvt_pk_bf16_f32 v177, v178, v179
	v_mfma_f32_16x16x32_bf16 v[92:95], v[228:231], v[136:139], v[92:95]
	v_cvt_pk_bf16_f32 v178, v232, v233
	v_cvt_pk_bf16_f32 v179, v234, v235
	v_add_f32_e32 v144, v144, v235
	v_add_f32_e32 v131, v131, v144
	s_waitcnt lgkmcnt(0)
; #define LAS __attribute__((address_space(3)))
; __device__ __forceinline__ s16x4 vtr(const LAS unsigned char* p) { return __builtin_bit_cast(s16x4, __builtin_amdgcn_ds_read_tr16_b64_v4i16((LAS v4i16_t*)p)); }
;     const int l15 = lane & 15, g = lane >> 4, q4 = l15 >> 2;
;     const LAS unsigned char* kb0 = Kt + l15 * 128;
;     const int kx0 = ((g) ^ (l15 & 7)) << 4, kx1 = ((4 + g) ^ (l15 & 7)) << 4;
;     const LAS unsigned char* vrow = Vt + (4 * g + q4) * 128 + (lane & 3) * 8;
;     const int swz = (2 * (g & 1) + (q4 >> 1)) & 3;
;     const f32x4 cinit = (f32x4){negb, negb, negb, negb};
; #pragma unroll
;     for (int gh = 0; gh < 4 / GPB; ++gh) {
;         f32x4 S[GPB][4];
; #pragma unroll
;         for (int kb = 0; kb < 4; ++kb) {
;             const bf16x8 kf0 = *(const LAS bf16x8*)(kb0 + (16 * kb) * 128 + kx0), kf1 = *(const LAS bf16x8*)(kb0 + (16 * kb) * 128 + kx1);
; #pragma unroll
;             for (int gi = 0; gi < GPB; ++gi) { S[gi][kb] = __builtin_amdgcn_mfma_f32_16x16x32_bf16(kf0, qf[GPB * gh + gi][0], cinit, 0, 0, 0);
;                 S[gi][kb] = __builtin_amdgcn_mfma_f32_16x16x32_bf16(kf1, qf[GPB * gh + gi][1], S[gi][kb], 0, 0, 0); } }
;         bf16x8 pf[GPB][2];
; #pragma unroll
;         for (int gi = 0; gi < GPB; ++gi) {
;             if (MASK) {
; #pragma unroll
;                 for (int kb = 0; kb < 4; ++kb)
; #pragma unroll
;                     for (int i = 0; i < 4; ++i) { const int rel = rel0 + 16 * kb + 4 * g + i; S[gi][kb][i] = ((unsigned)(rel + 128) > 256u) ? NEGBIG : S[gi][kb][i]; }
;             }
;             ls[GPB * gh + gi] += exp_step<4>(S[gi]);
;             pf[gi][0] = pack8(S[gi][0], S[gi][1]); pf[gi][1] = pack8(S[gi][2], S[gi][3]);
;         }
; #pragma unroll
;         for (int kc = 0; kc < 2; ++kc)
; #pragma unroll
;             for (int db = 0; db < 4; ++db) {
;                 const LAS unsigned char* va = vrow + ((db ^ swz) << 5) + (32 * kc) * 128;
;                 const bf16x8 vf = cat8(vtr(va), vtr(va + 16 * 128));
; #pragma unroll
;                 for (int gi = 0; gi < GPB; ++gi) O[GPB * gh + gi][db] = __builtin_amdgcn_mfma_f32_16x16x32_bf16(vf, pf[gi][kc], O[GPB * gh + gi][db], 0, 0, 0);
;             }
;         if (SB == 1) __builtin_amdgcn_sched_barrier(0); else if (SB == 2) __builtin_amdgcn_sched_barrier(0x108);
;     }
; }
	v_mfma_f32_16x16x32_bf16 v[136:139], v[104:107], v[20:23], v[0:3]
	v_exp_f32_e32 v244, v244
	v_exp_f32_e32 v245, v245
	v_mfma_f32_16x16x32_bf16 v[140:143], v[112:115], v[20:23], v[0:3]
	v_exp_f32_e32 v246, v246
	v_add_f32_e32 v144, v244, v245
	v_mfma_f32_16x16x32_bf16 v[136:139], v[108:111], v[24:27], v[136:139]
	v_exp_f32_e32 v247, v247
	v_add_f32_e32 v144, v144, v246
	v_mfma_f32_16x16x32_bf16 v[140:143], v[116:119], v[24:27], v[140:143]
	v_exp_f32_e32 v248, v248
	v_add_f32_e32 v144, v144, v247
	v_mfma_f32_16x16x32_bf16 v[64:67], v[160:163], v[176:179], v[64:67]
	v_exp_f32_e32 v249, v249
	v_add_f32_e32 v144, v144, v248
	v_mfma_f32_16x16x32_bf16 v[60:63], v[164:167], v[176:179], v[60:63]
	v_exp_f32_e32 v250, v250
	v_add_f32_e32 v144, v144, v249
	v_cvt_pk_bf16_f32 v244, v244, v245
	v_mfma_f32_16x16x32_bf16 v[56:59], v[168:171], v[176:179], v[56:59]
	v_exp_f32_e32 v251, v251
	v_add_f32_e32 v144, v144, v250
	v_cvt_pk_bf16_f32 v245, v246, v247
	v_mfma_f32_16x16x32_bf16 v[52:55], v[172:175], v[176:179], v[52:55]
	v_cvt_pk_bf16_f32 v246, v248, v249
	v_cvt_pk_bf16_f32 v247, v250, v251
	v_add_f32_e32 v144, v144, v251
	v_add_f32_e32 v130, v130, v144
	v_mfma_f32_16x16x32_bf16 v[176:179], v[104:107], v[28:31], v[0:3]
	v_exp_f32_e32 v136, v136
	v_exp_f32_e32 v137, v137
	v_mfma_f32_16x16x32_bf16 v[232:235], v[112:115], v[28:31], v[0:3]
	v_exp_f32_e32 v138, v138
	v_add_f32_e32 v144, v136, v137
	v_mfma_f32_16x16x32_bf16 v[176:179], v[108:111], v[32:35], v[176:179]
	v_exp_f32_e32 v139, v139
	v_add_f32_e32 v144, v144, v138
	v_mfma_f32_16x16x32_bf16 v[232:235], v[116:119], v[32:35], v[232:235]
	v_exp_f32_e32 v140, v140
	v_add_f32_e32 v144, v144, v139
	v_mfma_f32_16x16x32_bf16 v[48:51], v[160:163], v[244:247], v[48:51]
	v_exp_f32_e32 v141, v141
	v_add_f32_e32 v144, v144, v140
	v_mfma_f32_16x16x32_bf16 v[44:47], v[164:167], v[244:247], v[44:47]
	v_exp_f32_e32 v142, v142
	v_add_f32_e32 v144, v144, v141
	v_cvt_pk_bf16_f32 v136, v136, v137
	v_mfma_f32_16x16x32_bf16 v[40:43], v[168:171], v[244:247], v[40:43]
	v_exp_f32_e32 v143, v143
	v_add_f32_e32 v144, v144, v142
	v_cvt_pk_bf16_f32 v137, v138, v139
	v_mfma_f32_16x16x32_bf16 v[36:39], v[172:175], v[244:247], v[36:39]
	v_cvt_pk_bf16_f32 v138, v140, v141
	v_cvt_pk_bf16_f32 v139, v142, v143
	v_add_f32_e32 v144, v144, v143
	v_add_f32_e32 v129, v129, v144
	v_mfma_f32_16x16x32_bf16 v[72:75], v[160:163], v[136:139], v[72:75]
	v_exp_f32_e32 v176, v176
	v_exp_f32_e32 v177, v177
	v_exp_f32_e32 v178, v178
	v_add_f32_e32 v144, v176, v177
	v_mfma_f32_16x16x32_bf16 v[84:87], v[164:167], v[136:139], v[84:87]
	v_exp_f32_e32 v179, v179
	v_add_f32_e32 v144, v144, v178
	v_exp_f32_e32 v232, v232
	v_add_f32_e32 v144, v144, v179
	v_mfma_f32_16x16x32_bf16 v[88:91], v[168:171], v[136:139], v[88:91]
	v_exp_f32_e32 v233, v233
	v_add_f32_e32 v144, v144, v232
	v_exp_f32_e32 v234, v234
	v_add_f32_e32 v144, v144, v233
	v_cvt_pk_bf16_f32 v176, v176, v177
	v_mfma_f32_16x16x32_bf16 v[96:99], v[172:175], v[136:139], v[96:99]
	v_exp_f32_e32 v235, v235
	v_add_f32_e32 v144, v144, v234
	v_cvt_pk_bf16_f32 v177, v178, v179
	v_cvt_pk_bf16_f32 v178, v232, v233
	v_cvt_pk_bf16_f32 v179, v234, v235
	v_add_f32_e32 v144, v144, v235
	v_add_f32_e32 v128, v128, v144
	v_mfma_f32_16x16x32_bf16 v[68:71], v[160:163], v[176:179], v[68:71]
	v_mfma_f32_16x16x32_bf16 v[76:79], v[164:167], v[176:179], v[76:79]
	v_mfma_f32_16x16x32_bf16 v[80:83], v[168:171], v[176:179], v[80:83]
	v_mfma_f32_16x16x32_bf16 v[92:95], v[172:175], v[176:179], v[92:95]
	s_branch .LBB0_354

; __global__ void __launch_bounds__(512, 2) fwd_megakernel(Args a) {
	.amdhsa_kernel _Z14fwd_megakernel4Args
		.amdhsa_group_segment_fixed_size 0
		.amdhsa_private_segment_fixed_size 0
		.amdhsa_kernarg_size 432
		.amdhsa_user_sgpr_count 2
		.amdhsa_user_sgpr_dispatch_ptr 0
		.amdhsa_user_sgpr_queue_ptr 0
		.amdhsa_user_sgpr_kernarg_segment_ptr 1
		.amdhsa_user_sgpr_dispatch_id 0
		.amdhsa_user_sgpr_kernarg_preload_length 0
		.amdhsa_user_sgpr_kernarg_preload_offset 0
		.amdhsa_user_sgpr_private_segment_size 0
		.amdhsa_uses_dynamic_stack 0
		.amdhsa_enable_private_segment 0
		.amdhsa_system_sgpr_workgroup_id_x 1
		.amdhsa_system_sgpr_workgroup_id_y 0
		.amdhsa_system_sgpr_workgroup_id_z 0
		.amdhsa_system_sgpr_workgroup_info 0
		.amdhsa_system_vgpr_workitem_id 2
		.amdhsa_next_free_vgpr 256
		.amdhsa_next_free_sgpr 98
		.amdhsa_accum_offset 256
		.amdhsa_reserve_vcc 1
		.amdhsa_float_round_mode_32 0
		.amdhsa_float_round_mode_16_64 0
		.amdhsa_float_denorm_mode_32 3
		.amdhsa_float_denorm_mode_16_64 3
		.amdhsa_dx10_clamp 1
		.amdhsa_ieee_mode 1
		.amdhsa_fp16_overflow 0
		.amdhsa_tg_split 0
		.amdhsa_exception_fp_ieee_invalid_op 0
		.amdhsa_exception_fp_denorm_src 0
		.amdhsa_exception_fp_ieee_div_zero 0
		.amdhsa_exception_fp_ieee_overflow 0
		.amdhsa_exception_fp_ieee_underflow 0
		.amdhsa_exception_fp_ieee_inexact 0
		.amdhsa_exception_int_div_zero 0
	.end_amdhsa_kernel

; __global__ void __launch_bounds__(512, 2) fwd_megakernel(Args a) {
amdhsa.kernels:
  - .agpr_count:     0
    .args:
      - .offset:         0
        .size:           176
        .value_kind:     by_value
      - .offset:         176
        .size:           4
        .value_kind:     hidden_block_count_x
      - .offset:         180
        .size:           4
        .value_kind:     hidden_block_count_y
      - .offset:         184
        .size:           4
        .value_kind:     hidden_block_count_z
      - .offset:         188
        .size:           2
        .value_kind:     hidden_group_size_x
      - .offset:         190
        .size:           2
        .value_kind:     hidden_group_size_y
      - .offset:         192
        .size:           2
        .value_kind:     hidden_group_size_z
      - .offset:         194
        .size:           2
        .value_kind:     hidden_remainder_x
      - .offset:         196
        .size:           2
        .value_kind:     hidden_remainder_y
      - .offset:         198
        .size:           2
        .value_kind:     hidden_remainder_z
      - .offset:         216
        .size:           8
        .value_kind:     hidden_global_offset_x
      - .offset:         224
        .size:           8
        .value_kind:     hidden_global_offset_y
      - .offset:         232
        .size:           8
        .value_kind:     hidden_global_offset_z
      - .offset:         240
        .size:           2
        .value_kind:     hidden_grid_dims
      - .offset:         264
        .size:           8
        .value_kind:     hidden_multigrid_sync_arg
      - .offset:         296
        .size:           4
        .value_kind:     hidden_dynamic_lds_size
    .group_segment_fixed_size: 0
    .kernarg_segment_align: 8
    .kernarg_segment_size: 432
    .language:       OpenCL C
    .language_version:
      - 2
      - 0
    .max_flat_workgroup_size: 512
    .name:           _Z14fwd_megakernel4Args
    .private_segment_fixed_size: 0
    .sgpr_count:     104
    .sgpr_spill_count: 117
    .symbol:         _Z14fwd_megakernel4Args.kd
    .uniform_work_group_size: 1
    .uses_dynamic_stack: false
    .vgpr_count:     256
    .vgpr_spill_count: 0
    .wavefront_size: 64
